# v14 + mid-compute-segment s_setprio 0/1 yield pair removed
# speedup vs baseline: 1.0025x; 1.0025x over previous
.LBB0_121:
	ds_read_b128 v[164:167], v131
	ds_read_b128 v[168:171], v131 offset:1024
	ds_read_b128 v[172:175], v131 offset:2048
	ds_read_b128 v[176:179], v131 offset:3072
	ds_read_b128 v[180:183], v160
	ds_read_b128 v[184:187], v160 offset:1024
	ds_read_b128 v[188:191], v160 offset:2048
	ds_read_b128 v[192:195], v160 offset:3072
	s_add_i32 s55, s52, 0xfffc0080
	s_cmp_eq_u32 s54, 12
	s_cselect_b32 s57, s16, s55
	s_cselect_b32 s56, s17, s53
	s_or_b32 s55, s57, 0x80
	s_mov_b32 m0, s40
	s_nop 0
	buffer_load_dwordx4 v156, s[12:15], s52 offen lds
	s_nop 0
	s_mov_b32 m0, s41
	s_nop 0
	buffer_load_dwordx4 v157, s[12:15], s52 offen lds
	ds_read_b128 v[196:199], v161
	ds_read_b128 v[200:203], v161 offset:1024
	ds_read_b128 v[204:207], v161 offset:2048
	ds_read_b128 v[208:211], v161 offset:3072
	ds_read_b128 v[212:215], v161 offset:4096
	ds_read_b128 v[216:219], v161 offset:5120
	ds_read_b128 v[220:223], v161 offset:6144
	ds_read_b128 v[224:227], v161 offset:7168
	s_waitcnt vmcnt(8)
	s_waitcnt lgkmcnt(0)
	s_barrier
	s_setprio 1
	s_waitcnt lgkmcnt(7)
	v_mfma_f32_16x16x32_bf16 v[126:129], v[164:167], v[196:199], v[126:129]
	v_mfma_f32_16x16x32_bf16 v[122:125], v[172:175], v[196:199], v[122:125]
	s_waitcnt lgkmcnt(5)
	v_mfma_f32_16x16x32_bf16 v[118:121], v[164:167], v[204:207], v[118:121]
	v_mfma_f32_16x16x32_bf16 v[110:113], v[172:175], v[204:207], v[110:113]
	s_waitcnt lgkmcnt(3)
	v_mfma_f32_16x16x32_bf16 v[102:105], v[164:167], v[212:215], v[102:105]
	v_mfma_f32_16x16x32_bf16 v[94:97], v[172:175], v[212:215], v[94:97]
	s_waitcnt lgkmcnt(1)
	v_mfma_f32_16x16x32_bf16 v[86:89], v[164:167], v[220:223], v[86:89]
	v_mfma_f32_16x16x32_bf16 v[78:81], v[172:175], v[220:223], v[78:81]
	v_mfma_f32_16x16x32_bf16 v[126:129], v[168:171], v[200:203], v[126:129]
	v_mfma_f32_16x16x32_bf16 v[122:125], v[176:179], v[200:203], v[122:125]
	v_mfma_f32_16x16x32_bf16 v[118:121], v[168:171], v[208:211], v[118:121]
	v_mfma_f32_16x16x32_bf16 v[110:113], v[176:179], v[208:211], v[110:113]
	v_mfma_f32_16x16x32_bf16 v[102:105], v[168:171], v[216:219], v[102:105]
	v_mfma_f32_16x16x32_bf16 v[94:97], v[176:179], v[216:219], v[94:97]
	s_waitcnt lgkmcnt(0)
	v_mfma_f32_16x16x32_bf16 v[86:89], v[168:171], v[224:227], v[86:89]
	v_mfma_f32_16x16x32_bf16 v[78:81], v[176:179], v[224:227], v[78:81]
	v_mfma_f32_16x16x32_bf16 v[114:117], v[180:183], v[196:199], v[114:117]
	v_mfma_f32_16x16x32_bf16 v[106:109], v[188:191], v[196:199], v[106:109]
	v_mfma_f32_16x16x32_bf16 v[98:101], v[180:183], v[204:207], v[98:101]
	v_mfma_f32_16x16x32_bf16 v[90:93], v[188:191], v[204:207], v[90:93]
	v_mfma_f32_16x16x32_bf16 v[82:85], v[180:183], v[212:215], v[82:85]
	v_mfma_f32_16x16x32_bf16 v[74:77], v[188:191], v[212:215], v[74:77]
	v_mfma_f32_16x16x32_bf16 v[70:73], v[180:183], v[220:223], v[70:73]
	v_mfma_f32_16x16x32_bf16 v[66:69], v[188:191], v[220:223], v[66:69]
	v_mfma_f32_16x16x32_bf16 v[114:117], v[184:187], v[200:203], v[114:117]
	v_mfma_f32_16x16x32_bf16 v[106:109], v[192:195], v[200:203], v[106:109]
	v_mfma_f32_16x16x32_bf16 v[98:101], v[184:187], v[208:211], v[98:101]
	v_mfma_f32_16x16x32_bf16 v[90:93], v[192:195], v[208:211], v[90:93]
	v_mfma_f32_16x16x32_bf16 v[82:85], v[184:187], v[216:219], v[82:85]
	v_mfma_f32_16x16x32_bf16 v[74:77], v[192:195], v[216:219], v[74:77]
	v_mfma_f32_16x16x32_bf16 v[70:73], v[184:187], v[224:227], v[70:73]
	v_mfma_f32_16x16x32_bf16 v[66:69], v[192:195], v[224:227], v[66:69]
	s_setprio 0
	s_barrier
	ds_read_b128 v[196:199], v161 offset:16384
	ds_read_b128 v[200:203], v161 offset:17408
	s_mov_b32 m0, s22
	s_nop 0
	buffer_load_dwordx4 v154, s[8:11], s56 offen lds
	ds_read_b128 v[204:207], v161 offset:18432
	ds_read_b128 v[208:211], v161 offset:19456
	s_add_i32 s58, s56, 0x40000
	s_mov_b32 m0, s23
	s_nop 0
	buffer_load_dwordx4 v155, s[8:11], s56 offen lds
	ds_read_b128 v[212:215], v161 offset:20480
	ds_read_b128 v[216:219], v161 offset:21504
	s_nop 0
	s_mov_b32 m0, s24
	s_nop 0
	buffer_load_dwordx4 v154, s[8:11], s58 offen lds
	ds_read_b128 v[220:223], v161 offset:22528
	ds_read_b128 v[224:227], v161 offset:23552
	s_nop 0
	s_mov_b32 m0, s25
	s_nop 0
	buffer_load_dwordx4 v155, s[8:11], s58 offen lds
	s_nop 0
	s_mov_b32 m0, s21
	s_nop 0
	buffer_load_dwordx4 v156, s[12:15], s57 offen lds
	s_nop 0
	s_mov_b32 m0, s27
	s_nop 0
	buffer_load_dwordx4 v157, s[12:15], s57 offen lds
	s_waitcnt vmcnt(8)
	s_waitcnt lgkmcnt(0)
	s_barrier
	s_setprio 1
	s_waitcnt lgkmcnt(7)
	v_mfma_f32_16x16x32_bf16 v[62:65], v[164:167], v[196:199], v[62:65]
	v_mfma_f32_16x16x32_bf16 v[58:61], v[172:175], v[196:199], v[58:61]
	s_waitcnt lgkmcnt(5)
	v_mfma_f32_16x16x32_bf16 v[54:57], v[164:167], v[204:207], v[54:57]
	v_mfma_f32_16x16x32_bf16 v[46:49], v[172:175], v[204:207], v[46:49]
	s_waitcnt lgkmcnt(3)
	v_mfma_f32_16x16x32_bf16 v[38:41], v[164:167], v[212:215], v[38:41]
	v_mfma_f32_16x16x32_bf16 v[30:33], v[172:175], v[212:215], v[30:33]
	s_waitcnt lgkmcnt(1)
	v_mfma_f32_16x16x32_bf16 v[22:25], v[164:167], v[220:223], v[22:25]
	v_mfma_f32_16x16x32_bf16 v[14:17], v[172:175], v[220:223], v[14:17]
	v_mfma_f32_16x16x32_bf16 v[62:65], v[168:171], v[200:203], v[62:65]
	v_mfma_f32_16x16x32_bf16 v[58:61], v[176:179], v[200:203], v[58:61]
	v_mfma_f32_16x16x32_bf16 v[54:57], v[168:171], v[208:211], v[54:57]
	v_mfma_f32_16x16x32_bf16 v[46:49], v[176:179], v[208:211], v[46:49]
	v_mfma_f32_16x16x32_bf16 v[38:41], v[168:171], v[216:219], v[38:41]
	v_mfma_f32_16x16x32_bf16 v[30:33], v[176:179], v[216:219], v[30:33]
	s_waitcnt lgkmcnt(0)
	v_mfma_f32_16x16x32_bf16 v[22:25], v[168:171], v[224:227], v[22:25]
	v_mfma_f32_16x16x32_bf16 v[14:17], v[176:179], v[224:227], v[14:17]
	v_mfma_f32_16x16x32_bf16 v[50:53], v[180:183], v[196:199], v[50:53]
	v_mfma_f32_16x16x32_bf16 v[42:45], v[188:191], v[196:199], v[42:45]
	v_mfma_f32_16x16x32_bf16 v[34:37], v[180:183], v[204:207], v[34:37]
	v_mfma_f32_16x16x32_bf16 v[26:29], v[188:191], v[204:207], v[26:29]
	v_mfma_f32_16x16x32_bf16 v[18:21], v[180:183], v[212:215], v[18:21]
	v_mfma_f32_16x16x32_bf16 v[10:13], v[188:191], v[212:215], v[10:13]
	v_mfma_f32_16x16x32_bf16 v[6:9], v[180:183], v[220:223], v[6:9]
	v_mfma_f32_16x16x32_bf16 v[2:5], v[188:191], v[220:223], v[2:5]
	v_mfma_f32_16x16x32_bf16 v[50:53], v[184:187], v[200:203], v[50:53]
	v_mfma_f32_16x16x32_bf16 v[42:45], v[192:195], v[200:203], v[42:45]
	v_mfma_f32_16x16x32_bf16 v[34:37], v[184:187], v[208:211], v[34:37]
	v_mfma_f32_16x16x32_bf16 v[26:29], v[192:195], v[208:211], v[26:29]
	v_mfma_f32_16x16x32_bf16 v[18:21], v[184:187], v[216:219], v[18:21]
	v_mfma_f32_16x16x32_bf16 v[10:13], v[192:195], v[216:219], v[10:13]
	v_mfma_f32_16x16x32_bf16 v[6:9], v[184:187], v[224:227], v[6:9]
	v_mfma_f32_16x16x32_bf16 v[2:5], v[192:195], v[224:227], v[2:5]
	s_setprio 0
	s_barrier
	ds_read_b128 v[164:167], v162
	ds_read_b128 v[168:171], v162 offset:1024
	ds_read_b128 v[172:175], v162 offset:2048
	ds_read_b128 v[176:179], v162 offset:3072
	ds_read_b128 v[180:183], v163
	ds_read_b128 v[184:187], v163 offset:1024
	ds_read_b128 v[188:191], v163 offset:2048
	ds_read_b128 v[192:195], v163 offset:3072
	s_add_i32 s57, s57, 0x40000
	s_mov_b32 m0, s28
	s_nop 0
	buffer_load_dwordx4 v156, s[12:15], s57 offen lds
	s_nop 0
	s_mov_b32 m0, s30
	s_nop 0
	buffer_load_dwordx4 v157, s[12:15], s57 offen lds
	ds_read_b128 v[196:199], v161 offset:32768
	ds_read_b128 v[200:203], v161 offset:33792
	ds_read_b128 v[204:207], v161 offset:34816
	ds_read_b128 v[208:211], v161 offset:35840
	ds_read_b128 v[212:215], v161 offset:36864
	ds_read_b128 v[216:219], v161 offset:37888
	ds_read_b128 v[220:223], v161 offset:38912
	ds_read_b128 v[224:227], v161 offset:39936
	s_waitcnt vmcnt(8)
	s_waitcnt lgkmcnt(0)
	s_barrier
	s_setprio 1
	s_waitcnt lgkmcnt(7)
	v_mfma_f32_16x16x32_bf16 v[126:129], v[164:167], v[196:199], v[126:129]
	v_mfma_f32_16x16x32_bf16 v[122:125], v[172:175], v[196:199], v[122:125]
	s_waitcnt lgkmcnt(5)
	v_mfma_f32_16x16x32_bf16 v[118:121], v[164:167], v[204:207], v[118:121]
	v_mfma_f32_16x16x32_bf16 v[110:113], v[172:175], v[204:207], v[110:113]
	s_waitcnt lgkmcnt(3)
	v_mfma_f32_16x16x32_bf16 v[102:105], v[164:167], v[212:215], v[102:105]
	v_mfma_f32_16x16x32_bf16 v[94:97], v[172:175], v[212:215], v[94:97]
	s_waitcnt lgkmcnt(1)
	v_mfma_f32_16x16x32_bf16 v[86:89], v[164:167], v[220:223], v[86:89]
	v_mfma_f32_16x16x32_bf16 v[78:81], v[172:175], v[220:223], v[78:81]
	v_mfma_f32_16x16x32_bf16 v[126:129], v[168:171], v[200:203], v[126:129]
	v_mfma_f32_16x16x32_bf16 v[122:125], v[176:179], v[200:203], v[122:125]
	v_mfma_f32_16x16x32_bf16 v[118:121], v[168:171], v[208:211], v[118:121]
	v_mfma_f32_16x16x32_bf16 v[110:113], v[176:179], v[208:211], v[110:113]
	v_mfma_f32_16x16x32_bf16 v[102:105], v[168:171], v[216:219], v[102:105]
	v_mfma_f32_16x16x32_bf16 v[94:97], v[176:179], v[216:219], v[94:97]
	s_waitcnt lgkmcnt(0)
	v_mfma_f32_16x16x32_bf16 v[86:89], v[168:171], v[224:227], v[86:89]
	v_mfma_f32_16x16x32_bf16 v[78:81], v[176:179], v[224:227], v[78:81]
	v_mfma_f32_16x16x32_bf16 v[114:117], v[180:183], v[196:199], v[114:117]
	v_mfma_f32_16x16x32_bf16 v[106:109], v[188:191], v[196:199], v[106:109]
	v_mfma_f32_16x16x32_bf16 v[98:101], v[180:183], v[204:207], v[98:101]
	v_mfma_f32_16x16x32_bf16 v[90:93], v[188:191], v[204:207], v[90:93]
	v_mfma_f32_16x16x32_bf16 v[82:85], v[180:183], v[212:215], v[82:85]
	v_mfma_f32_16x16x32_bf16 v[74:77], v[188:191], v[212:215], v[74:77]
	v_mfma_f32_16x16x32_bf16 v[70:73], v[180:183], v[220:223], v[70:73]
	v_mfma_f32_16x16x32_bf16 v[66:69], v[188:191], v[220:223], v[66:69]
	v_mfma_f32_16x16x32_bf16 v[114:117], v[184:187], v[200:203], v[114:117]
	v_mfma_f32_16x16x32_bf16 v[106:109], v[192:195], v[200:203], v[106:109]
	v_mfma_f32_16x16x32_bf16 v[98:101], v[184:187], v[208:211], v[98:101]
	v_mfma_f32_16x16x32_bf16 v[90:93], v[192:195], v[208:211], v[90:93]
	v_mfma_f32_16x16x32_bf16 v[82:85], v[184:187], v[216:219], v[82:85]
	v_mfma_f32_16x16x32_bf16 v[74:77], v[192:195], v[216:219], v[74:77]
	v_mfma_f32_16x16x32_bf16 v[70:73], v[184:187], v[224:227], v[70:73]
	v_mfma_f32_16x16x32_bf16 v[66:69], v[192:195], v[224:227], v[66:69]
	s_setprio 0
	s_barrier
	ds_read_b128 v[196:199], v161 offset:49152
	ds_read_b128 v[200:203], v161 offset:50176
	s_or_b32 s57, s56, 0x80
	s_mov_b32 m0, s34
	s_nop 0
	buffer_load_dwordx4 v154, s[8:11], s57 offen lds
	ds_read_b128 v[204:207], v161 offset:51200
	ds_read_b128 v[208:211], v161 offset:52224
	s_add_i32 s56, s56, 0x40080
	s_mov_b32 m0, s35
	s_nop 0
	buffer_load_dwordx4 v155, s[8:11], s57 offen lds
	ds_read_b128 v[212:215], v161 offset:53248
	ds_read_b128 v[216:219], v161 offset:54272
	s_nop 0
	s_mov_b32 m0, s38
	s_nop 0
	buffer_load_dwordx4 v154, s[8:11], s56 offen lds
	ds_read_b128 v[220:223], v161 offset:55296
	ds_read_b128 v[224:227], v161 offset:56320
	s_nop 0
	s_mov_b32 m0, s39
	s_nop 0
	buffer_load_dwordx4 v155, s[8:11], s56 offen lds
	s_nop 0
	s_mov_b32 m0, s36
	s_nop 0
	buffer_load_dwordx4 v156, s[12:15], s55 offen lds
	s_nop 0
	s_mov_b32 m0, s37
	s_nop 0
	buffer_load_dwordx4 v157, s[12:15], s55 offen lds
	s_waitcnt vmcnt(8)
	s_waitcnt lgkmcnt(0)
	s_barrier
	s_setprio 1
	s_waitcnt lgkmcnt(7)
	v_mfma_f32_16x16x32_bf16 v[62:65], v[164:167], v[196:199], v[62:65]
	v_mfma_f32_16x16x32_bf16 v[58:61], v[172:175], v[196:199], v[58:61]
	s_waitcnt lgkmcnt(5)
	v_mfma_f32_16x16x32_bf16 v[54:57], v[164:167], v[204:207], v[54:57]
	v_mfma_f32_16x16x32_bf16 v[46:49], v[172:175], v[204:207], v[46:49]
	s_waitcnt lgkmcnt(3)
	v_mfma_f32_16x16x32_bf16 v[38:41], v[164:167], v[212:215], v[38:41]
	v_mfma_f32_16x16x32_bf16 v[30:33], v[172:175], v[212:215], v[30:33]
	s_waitcnt lgkmcnt(1)
	v_mfma_f32_16x16x32_bf16 v[22:25], v[164:167], v[220:223], v[22:25]
	v_mfma_f32_16x16x32_bf16 v[14:17], v[172:175], v[220:223], v[14:17]
	v_mfma_f32_16x16x32_bf16 v[62:65], v[168:171], v[200:203], v[62:65]
	v_mfma_f32_16x16x32_bf16 v[58:61], v[176:179], v[200:203], v[58:61]
	v_mfma_f32_16x16x32_bf16 v[54:57], v[168:171], v[208:211], v[54:57]
	v_mfma_f32_16x16x32_bf16 v[46:49], v[176:179], v[208:211], v[46:49]
	v_mfma_f32_16x16x32_bf16 v[38:41], v[168:171], v[216:219], v[38:41]
	v_mfma_f32_16x16x32_bf16 v[30:33], v[176:179], v[216:219], v[30:33]
	s_waitcnt lgkmcnt(0)
	v_mfma_f32_16x16x32_bf16 v[22:25], v[168:171], v[224:227], v[22:25]
	v_mfma_f32_16x16x32_bf16 v[14:17], v[176:179], v[224:227], v[14:17]
	v_mfma_f32_16x16x32_bf16 v[50:53], v[180:183], v[196:199], v[50:53]
	v_mfma_f32_16x16x32_bf16 v[42:45], v[188:191], v[196:199], v[42:45]
	v_mfma_f32_16x16x32_bf16 v[34:37], v[180:183], v[204:207], v[34:37]
	v_mfma_f32_16x16x32_bf16 v[26:29], v[188:191], v[204:207], v[26:29]
	v_mfma_f32_16x16x32_bf16 v[18:21], v[180:183], v[212:215], v[18:21]
	v_mfma_f32_16x16x32_bf16 v[10:13], v[188:191], v[212:215], v[10:13]
	v_mfma_f32_16x16x32_bf16 v[6:9], v[180:183], v[220:223], v[6:9]
	v_mfma_f32_16x16x32_bf16 v[2:5], v[188:191], v[220:223], v[2:5]
	v_mfma_f32_16x16x32_bf16 v[50:53], v[184:187], v[200:203], v[50:53]
	v_mfma_f32_16x16x32_bf16 v[42:45], v[192:195], v[200:203], v[42:45]
	v_mfma_f32_16x16x32_bf16 v[34:37], v[184:187], v[208:211], v[34:37]
	v_mfma_f32_16x16x32_bf16 v[26:29], v[192:195], v[208:211], v[26:29]
	v_mfma_f32_16x16x32_bf16 v[18:21], v[184:187], v[216:219], v[18:21]
	v_mfma_f32_16x16x32_bf16 v[10:13], v[192:195], v[216:219], v[10:13]
	v_mfma_f32_16x16x32_bf16 v[6:9], v[184:187], v[224:227], v[6:9]
	v_mfma_f32_16x16x32_bf16 v[2:5], v[192:195], v[224:227], v[2:5]
	s_setprio 0
	s_barrier
	s_add_i32 s54, s54, 2
	s_addk_i32 s52, 0x100
	s_addk_i32 s53, 0x100
	s_cmp_gt_u32 s54, 13
	s_cbranch_scc0 .LBB0_121
	s_and_b64 vcc, exec, s[6:7]
	s_cbranch_vccz .LBB0_126
	s_barrier
	s_cmp_gt_i32 s46, 3
	s_mov_b64 s[16:17], -1
	s_cbranch_scc1 .LBB0_127

.LBB0_223:
	v_add_u32_e32 v150, 0x10000, v132
	v_add_u32_e32 v166, 0x14000, v132
	ds_read_b128 v[134:137], v150
	ds_read_b128 v[142:145], v150 offset:1024
	ds_read_b128 v[146:149], v150 offset:2048
	ds_read_b128 v[150:153], v150 offset:3072
	ds_read_b128 v[154:157], v166
	ds_read_b128 v[158:161], v166 offset:1024
	ds_read_b128 v[162:165], v166 offset:2048
	ds_read_b128 v[166:169], v166 offset:3072
	s_add_i32 s63, s39, s60
	s_add_i32 s62, s34, s60
	s_add_i32 s61, s63, 0x800
	s_addk_i32 s62, 0x800
	s_cmp_eq_u32 s60, 0
	s_cselect_b32 s64, s55, s61
	s_cselect_b32 s62, s58, s62
	s_or_b32 s61, s64, 0x80
	s_add_i32 s63, s63, 0x40780
	s_mov_b32 m0, s49
	s_nop 0
	buffer_load_dwordx4 v130, s[12:15], s63 offen lds
	s_nop 0
	s_mov_b32 m0, s50
	s_nop 0
	buffer_load_dwordx4 v131, s[12:15], s63 offen lds
	ds_read_b128 v[170:173], v133
	ds_read_b128 v[174:177], v133 offset:1024
	ds_read_b128 v[178:181], v133 offset:2048
	ds_read_b128 v[182:185], v133 offset:3072
	ds_read_b128 v[186:189], v133 offset:4096
	ds_read_b128 v[190:193], v133 offset:5120
	ds_read_b128 v[194:197], v133 offset:6144
	ds_read_b128 v[198:201], v133 offset:7168
	s_waitcnt vmcnt(8)
	s_waitcnt lgkmcnt(0)
	s_barrier
	s_setprio 1
	s_waitcnt lgkmcnt(7)
	v_mfma_f32_16x16x32_bf16 v[138:141], v[134:137], v[170:173], v[138:141]
	v_mfma_f32_16x16x32_bf16 v[126:129], v[146:149], v[170:173], v[126:129]
	s_waitcnt lgkmcnt(5)
	v_mfma_f32_16x16x32_bf16 v[110:113], v[134:137], v[178:181], v[110:113]
	v_mfma_f32_16x16x32_bf16 v[106:109], v[146:149], v[178:181], v[106:109]
	s_waitcnt lgkmcnt(3)
	v_mfma_f32_16x16x32_bf16 v[94:97], v[134:137], v[186:189], v[94:97]
	v_mfma_f32_16x16x32_bf16 v[90:93], v[146:149], v[186:189], v[90:93]
	s_waitcnt lgkmcnt(1)
	v_mfma_f32_16x16x32_bf16 v[78:81], v[134:137], v[194:197], v[78:81]
	v_mfma_f32_16x16x32_bf16 v[74:77], v[146:149], v[194:197], v[74:77]
	v_mfma_f32_16x16x32_bf16 v[138:141], v[142:145], v[174:177], v[138:141]
	v_mfma_f32_16x16x32_bf16 v[126:129], v[150:153], v[174:177], v[126:129]
	v_mfma_f32_16x16x32_bf16 v[110:113], v[142:145], v[182:185], v[110:113]
	v_mfma_f32_16x16x32_bf16 v[106:109], v[150:153], v[182:185], v[106:109]
	v_mfma_f32_16x16x32_bf16 v[94:97], v[142:145], v[190:193], v[94:97]
	v_mfma_f32_16x16x32_bf16 v[90:93], v[150:153], v[190:193], v[90:93]
	s_waitcnt lgkmcnt(0)
	v_mfma_f32_16x16x32_bf16 v[78:81], v[142:145], v[198:201], v[78:81]
	v_mfma_f32_16x16x32_bf16 v[74:77], v[150:153], v[198:201], v[74:77]
	v_mfma_f32_16x16x32_bf16 v[118:121], v[154:157], v[170:173], v[118:121]
	v_mfma_f32_16x16x32_bf16 v[114:117], v[162:165], v[170:173], v[114:117]
	v_mfma_f32_16x16x32_bf16 v[102:105], v[154:157], v[178:181], v[102:105]
	v_mfma_f32_16x16x32_bf16 v[98:101], v[162:165], v[178:181], v[98:101]
	v_mfma_f32_16x16x32_bf16 v[86:89], v[154:157], v[186:189], v[86:89]
	v_mfma_f32_16x16x32_bf16 v[82:85], v[162:165], v[186:189], v[82:85]
	v_mfma_f32_16x16x32_bf16 v[70:73], v[154:157], v[194:197], v[70:73]
	v_mfma_f32_16x16x32_bf16 v[66:69], v[162:165], v[194:197], v[66:69]
	v_mfma_f32_16x16x32_bf16 v[118:121], v[158:161], v[174:177], v[118:121]
	v_mfma_f32_16x16x32_bf16 v[114:117], v[166:169], v[174:177], v[114:117]
	v_mfma_f32_16x16x32_bf16 v[102:105], v[158:161], v[182:185], v[102:105]
	v_mfma_f32_16x16x32_bf16 v[98:101], v[166:169], v[182:185], v[98:101]
	v_mfma_f32_16x16x32_bf16 v[86:89], v[158:161], v[190:193], v[86:89]
	v_mfma_f32_16x16x32_bf16 v[82:85], v[166:169], v[190:193], v[82:85]
	v_mfma_f32_16x16x32_bf16 v[70:73], v[158:161], v[198:201], v[70:73]
	v_mfma_f32_16x16x32_bf16 v[66:69], v[166:169], v[198:201], v[66:69]
	s_setprio 0
	s_barrier
	ds_read_b128 v[170:173], v133 offset:16384
	ds_read_b128 v[174:177], v133 offset:17408
	s_mov_b32 m0, s33
	s_nop 0
	buffer_load_dwordx4 v130, s[8:11], s62 offen lds
	ds_read_b128 v[178:181], v133 offset:18432
	ds_read_b128 v[182:185], v133 offset:19456
	s_add_i32 s63, s62, 0x40000
	s_mov_b32 m0, s35
	s_nop 0
	buffer_load_dwordx4 v131, s[8:11], s62 offen lds
	ds_read_b128 v[186:189], v133 offset:20480
	ds_read_b128 v[190:193], v133 offset:21504
	s_nop 0
	s_mov_b32 m0, s36
	s_nop 0
	buffer_load_dwordx4 v130, s[8:11], s63 offen lds
	ds_read_b128 v[194:197], v133 offset:22528
	ds_read_b128 v[198:201], v133 offset:23552
	s_nop 0
	s_mov_b32 m0, s37
	s_nop 0
	buffer_load_dwordx4 v131, s[8:11], s63 offen lds
	s_nop 0
	s_mov_b32 m0, s31
	s_nop 0
	buffer_load_dwordx4 v130, s[12:15], s64 offen lds
	s_nop 0
	s_mov_b32 m0, s40
	s_nop 0
	buffer_load_dwordx4 v131, s[12:15], s64 offen lds
	s_waitcnt vmcnt(8)
	s_waitcnt lgkmcnt(0)
	s_barrier
	s_setprio 1
	s_waitcnt lgkmcnt(7)
	v_mfma_f32_16x16x32_bf16 v[62:65], v[134:137], v[170:173], v[62:65]
	v_mfma_f32_16x16x32_bf16 v[58:61], v[146:149], v[170:173], v[58:61]
	s_waitcnt lgkmcnt(5)
	v_mfma_f32_16x16x32_bf16 v[46:49], v[134:137], v[178:181], v[46:49]
	v_mfma_f32_16x16x32_bf16 v[42:45], v[146:149], v[178:181], v[42:45]
	s_waitcnt lgkmcnt(3)
	v_mfma_f32_16x16x32_bf16 v[30:33], v[134:137], v[186:189], v[30:33]
	v_mfma_f32_16x16x32_bf16 v[26:29], v[146:149], v[186:189], v[26:29]
	s_waitcnt lgkmcnt(1)
	v_mfma_f32_16x16x32_bf16 v[14:17], v[134:137], v[194:197], v[14:17]
	v_mfma_f32_16x16x32_bf16 v[10:13], v[146:149], v[194:197], v[10:13]
	v_mfma_f32_16x16x32_bf16 v[62:65], v[142:145], v[174:177], v[62:65]
	v_mfma_f32_16x16x32_bf16 v[58:61], v[150:153], v[174:177], v[58:61]
	v_mfma_f32_16x16x32_bf16 v[46:49], v[142:145], v[182:185], v[46:49]
	v_mfma_f32_16x16x32_bf16 v[42:45], v[150:153], v[182:185], v[42:45]
	v_mfma_f32_16x16x32_bf16 v[30:33], v[142:145], v[190:193], v[30:33]
	v_mfma_f32_16x16x32_bf16 v[26:29], v[150:153], v[190:193], v[26:29]
	s_waitcnt lgkmcnt(0)
	v_mfma_f32_16x16x32_bf16 v[14:17], v[142:145], v[198:201], v[14:17]
	v_mfma_f32_16x16x32_bf16 v[10:13], v[150:153], v[198:201], v[10:13]
	v_mfma_f32_16x16x32_bf16 v[54:57], v[154:157], v[170:173], v[54:57]
	v_mfma_f32_16x16x32_bf16 v[50:53], v[162:165], v[170:173], v[50:53]
	v_mfma_f32_16x16x32_bf16 v[38:41], v[154:157], v[178:181], v[38:41]
	v_mfma_f32_16x16x32_bf16 v[34:37], v[162:165], v[178:181], v[34:37]
	v_mfma_f32_16x16x32_bf16 v[22:25], v[154:157], v[186:189], v[22:25]
	v_mfma_f32_16x16x32_bf16 v[18:21], v[162:165], v[186:189], v[18:21]
	v_mfma_f32_16x16x32_bf16 v[6:9], v[154:157], v[194:197], v[6:9]
	v_mfma_f32_16x16x32_bf16 v[2:5], v[162:165], v[194:197], v[2:5]
	v_mfma_f32_16x16x32_bf16 v[54:57], v[158:161], v[174:177], v[54:57]
	v_mfma_f32_16x16x32_bf16 v[50:53], v[166:169], v[174:177], v[50:53]
	v_mfma_f32_16x16x32_bf16 v[38:41], v[158:161], v[182:185], v[38:41]
	v_mfma_f32_16x16x32_bf16 v[34:37], v[166:169], v[182:185], v[34:37]
	v_mfma_f32_16x16x32_bf16 v[22:25], v[158:161], v[190:193], v[22:25]
	v_mfma_f32_16x16x32_bf16 v[18:21], v[166:169], v[190:193], v[18:21]
	v_mfma_f32_16x16x32_bf16 v[6:9], v[158:161], v[198:201], v[6:9]
	v_mfma_f32_16x16x32_bf16 v[2:5], v[166:169], v[198:201], v[2:5]
	s_setprio 0
	s_barrier
	v_add_u32_e32 v150, 0x18000, v132
	v_add_u32_e32 v166, 0x1c000, v132
	ds_read_b128 v[134:137], v150
	ds_read_b128 v[142:145], v150 offset:1024
	ds_read_b128 v[146:149], v150 offset:2048
	ds_read_b128 v[150:153], v150 offset:3072
	ds_read_b128 v[154:157], v166
	ds_read_b128 v[158:161], v166 offset:1024
	ds_read_b128 v[162:165], v166 offset:2048
	ds_read_b128 v[166:169], v166 offset:3072
	s_add_i32 s63, s64, 0x40000
	s_mov_b32 m0, s41
	s_nop 0
	buffer_load_dwordx4 v130, s[12:15], s63 offen lds
	s_nop 0
	s_mov_b32 m0, s42
	s_nop 0
	buffer_load_dwordx4 v131, s[12:15], s63 offen lds
	ds_read_b128 v[170:173], v133 offset:32768
	ds_read_b128 v[174:177], v133 offset:33792
	ds_read_b128 v[178:181], v133 offset:34816
	ds_read_b128 v[182:185], v133 offset:35840
	ds_read_b128 v[186:189], v133 offset:36864
	ds_read_b128 v[190:193], v133 offset:37888
	ds_read_b128 v[194:197], v133 offset:38912
	ds_read_b128 v[198:201], v133 offset:39936
	s_waitcnt vmcnt(8)
	s_waitcnt lgkmcnt(0)
	s_barrier
	s_setprio 1
	s_waitcnt lgkmcnt(7)
	v_mfma_f32_16x16x32_bf16 v[138:141], v[134:137], v[170:173], v[138:141]
	v_mfma_f32_16x16x32_bf16 v[126:129], v[146:149], v[170:173], v[126:129]
	s_waitcnt lgkmcnt(5)
	v_mfma_f32_16x16x32_bf16 v[110:113], v[134:137], v[178:181], v[110:113]
	v_mfma_f32_16x16x32_bf16 v[106:109], v[146:149], v[178:181], v[106:109]
	s_waitcnt lgkmcnt(3)
	v_mfma_f32_16x16x32_bf16 v[94:97], v[134:137], v[186:189], v[94:97]
	v_mfma_f32_16x16x32_bf16 v[90:93], v[146:149], v[186:189], v[90:93]
	s_waitcnt lgkmcnt(1)
	v_mfma_f32_16x16x32_bf16 v[78:81], v[134:137], v[194:197], v[78:81]
	v_mfma_f32_16x16x32_bf16 v[74:77], v[146:149], v[194:197], v[74:77]
	v_mfma_f32_16x16x32_bf16 v[138:141], v[142:145], v[174:177], v[138:141]
	v_mfma_f32_16x16x32_bf16 v[126:129], v[150:153], v[174:177], v[126:129]
	v_mfma_f32_16x16x32_bf16 v[110:113], v[142:145], v[182:185], v[110:113]
	v_mfma_f32_16x16x32_bf16 v[106:109], v[150:153], v[182:185], v[106:109]
	v_mfma_f32_16x16x32_bf16 v[94:97], v[142:145], v[190:193], v[94:97]
	v_mfma_f32_16x16x32_bf16 v[90:93], v[150:153], v[190:193], v[90:93]
	s_waitcnt lgkmcnt(0)
	v_mfma_f32_16x16x32_bf16 v[78:81], v[142:145], v[198:201], v[78:81]
	v_mfma_f32_16x16x32_bf16 v[74:77], v[150:153], v[198:201], v[74:77]
	v_mfma_f32_16x16x32_bf16 v[118:121], v[154:157], v[170:173], v[118:121]
	v_mfma_f32_16x16x32_bf16 v[114:117], v[162:165], v[170:173], v[114:117]
	v_mfma_f32_16x16x32_bf16 v[102:105], v[154:157], v[178:181], v[102:105]
	v_mfma_f32_16x16x32_bf16 v[98:101], v[162:165], v[178:181], v[98:101]
	v_mfma_f32_16x16x32_bf16 v[86:89], v[154:157], v[186:189], v[86:89]
	v_mfma_f32_16x16x32_bf16 v[82:85], v[162:165], v[186:189], v[82:85]
	v_mfma_f32_16x16x32_bf16 v[70:73], v[154:157], v[194:197], v[70:73]
	v_mfma_f32_16x16x32_bf16 v[66:69], v[162:165], v[194:197], v[66:69]
	v_mfma_f32_16x16x32_bf16 v[118:121], v[158:161], v[174:177], v[118:121]
	v_mfma_f32_16x16x32_bf16 v[114:117], v[166:169], v[174:177], v[114:117]
	v_mfma_f32_16x16x32_bf16 v[102:105], v[158:161], v[182:185], v[102:105]
	v_mfma_f32_16x16x32_bf16 v[98:101], v[166:169], v[182:185], v[98:101]
	v_mfma_f32_16x16x32_bf16 v[86:89], v[158:161], v[190:193], v[86:89]
	v_mfma_f32_16x16x32_bf16 v[82:85], v[166:169], v[190:193], v[82:85]
	v_mfma_f32_16x16x32_bf16 v[70:73], v[158:161], v[198:201], v[70:73]
	v_mfma_f32_16x16x32_bf16 v[66:69], v[166:169], v[198:201], v[66:69]
	s_setprio 0
	s_barrier
	ds_read_b128 v[170:173], v133 offset:49152
	ds_read_b128 v[174:177], v133 offset:50176
	s_or_b32 s63, s62, 0x80
	s_mov_b32 m0, s43
	s_nop 0
	buffer_load_dwordx4 v130, s[8:11], s63 offen lds
	ds_read_b128 v[178:181], v133 offset:51200
	ds_read_b128 v[182:185], v133 offset:52224
	s_add_i32 s62, s62, 0x40080
	s_mov_b32 m0, s44
	s_nop 0
	buffer_load_dwordx4 v131, s[8:11], s63 offen lds
	ds_read_b128 v[186:189], v133 offset:53248
	ds_read_b128 v[190:193], v133 offset:54272
	s_nop 0
	s_mov_b32 m0, s47
	s_nop 0
	buffer_load_dwordx4 v130, s[8:11], s62 offen lds
	ds_read_b128 v[194:197], v133 offset:55296
	ds_read_b128 v[198:201], v133 offset:56320
	s_nop 0
	s_mov_b32 m0, s48
	s_nop 0
	buffer_load_dwordx4 v131, s[8:11], s62 offen lds
	s_nop 0
	s_mov_b32 m0, s45
	s_nop 0
	buffer_load_dwordx4 v130, s[12:15], s61 offen lds
	s_nop 0
	s_mov_b32 m0, s46
	s_nop 0
	buffer_load_dwordx4 v131, s[12:15], s61 offen lds
	s_waitcnt vmcnt(8)
	s_waitcnt lgkmcnt(0)
	s_barrier
	s_setprio 1
	s_waitcnt lgkmcnt(7)
	v_mfma_f32_16x16x32_bf16 v[62:65], v[134:137], v[170:173], v[62:65]
	v_mfma_f32_16x16x32_bf16 v[58:61], v[146:149], v[170:173], v[58:61]
	s_waitcnt lgkmcnt(5)
	v_mfma_f32_16x16x32_bf16 v[46:49], v[134:137], v[178:181], v[46:49]
	v_mfma_f32_16x16x32_bf16 v[42:45], v[146:149], v[178:181], v[42:45]
	s_waitcnt lgkmcnt(3)
	v_mfma_f32_16x16x32_bf16 v[30:33], v[134:137], v[186:189], v[30:33]
	v_mfma_f32_16x16x32_bf16 v[26:29], v[146:149], v[186:189], v[26:29]
	s_waitcnt lgkmcnt(1)
	v_mfma_f32_16x16x32_bf16 v[14:17], v[134:137], v[194:197], v[14:17]
	v_mfma_f32_16x16x32_bf16 v[10:13], v[146:149], v[194:197], v[10:13]
	v_mfma_f32_16x16x32_bf16 v[62:65], v[142:145], v[174:177], v[62:65]
	v_mfma_f32_16x16x32_bf16 v[58:61], v[150:153], v[174:177], v[58:61]
	v_mfma_f32_16x16x32_bf16 v[46:49], v[142:145], v[182:185], v[46:49]
	v_mfma_f32_16x16x32_bf16 v[42:45], v[150:153], v[182:185], v[42:45]
	v_mfma_f32_16x16x32_bf16 v[30:33], v[142:145], v[190:193], v[30:33]
	v_mfma_f32_16x16x32_bf16 v[26:29], v[150:153], v[190:193], v[26:29]
	s_waitcnt lgkmcnt(0)
	v_mfma_f32_16x16x32_bf16 v[14:17], v[142:145], v[198:201], v[14:17]
	v_mfma_f32_16x16x32_bf16 v[10:13], v[150:153], v[198:201], v[10:13]
	v_mfma_f32_16x16x32_bf16 v[54:57], v[154:157], v[170:173], v[54:57]
	v_mfma_f32_16x16x32_bf16 v[50:53], v[162:165], v[170:173], v[50:53]
	v_mfma_f32_16x16x32_bf16 v[38:41], v[154:157], v[178:181], v[38:41]
	v_mfma_f32_16x16x32_bf16 v[34:37], v[162:165], v[178:181], v[34:37]
	v_mfma_f32_16x16x32_bf16 v[22:25], v[154:157], v[186:189], v[22:25]
	v_mfma_f32_16x16x32_bf16 v[18:21], v[162:165], v[186:189], v[18:21]
	v_mfma_f32_16x16x32_bf16 v[6:9], v[154:157], v[194:197], v[6:9]
	v_mfma_f32_16x16x32_bf16 v[2:5], v[162:165], v[194:197], v[2:5]
	v_mfma_f32_16x16x32_bf16 v[54:57], v[158:161], v[174:177], v[54:57]
	v_mfma_f32_16x16x32_bf16 v[50:53], v[166:169], v[174:177], v[50:53]
	v_mfma_f32_16x16x32_bf16 v[38:41], v[158:161], v[182:185], v[38:41]
	v_mfma_f32_16x16x32_bf16 v[34:37], v[166:169], v[182:185], v[34:37]
	v_mfma_f32_16x16x32_bf16 v[22:25], v[158:161], v[190:193], v[22:25]
	v_mfma_f32_16x16x32_bf16 v[18:21], v[166:169], v[190:193], v[18:21]
	v_mfma_f32_16x16x32_bf16 v[6:9], v[158:161], v[198:201], v[6:9]
	v_mfma_f32_16x16x32_bf16 v[2:5], v[166:169], v[198:201], v[2:5]
	s_setprio 0
	s_barrier
	s_add_i32 s59, s59, 2
	s_addk_i32 s60, 0x100
	s_cmp_gt_u32 s59, 13
	s_cbranch_scc0 .LBB0_223
	s_andn2_b64 vcc, exec, s[6:7]
	s_cbranch_vccnz .LBB0_215
	v_mov_b32_e32 v2, 0
	s_mov_b32 s18, s52
	s_mov_b32 s29, s53
	s_mov_b32 s34, s3
	s_mov_b32 s39, s2
	s_mov_b32 s51, s54
	v_mov_b32_e32 v3, v2
	v_mov_b32_e32 v4, v2
	v_mov_b32_e32 v5, v2
	v_mov_b32_e32 v6, v2
	v_mov_b32_e32 v7, v2
	v_mov_b32_e32 v8, v2
	v_mov_b32_e32 v9, v2
	v_mov_b32_e32 v18, v2
	v_mov_b32_e32 v19, v2
	v_mov_b32_e32 v20, v2
	v_mov_b32_e32 v21, v2
	v_mov_b32_e32 v22, v2
	v_mov_b32_e32 v23, v2
	v_mov_b32_e32 v24, v2
	v_mov_b32_e32 v25, v2
	v_mov_b32_e32 v34, v2
	v_mov_b32_e32 v35, v2
	v_mov_b32_e32 v36, v2
	v_mov_b32_e32 v37, v2
	v_mov_b32_e32 v38, v2
	v_mov_b32_e32 v39, v2
	v_mov_b32_e32 v40, v2
	v_mov_b32_e32 v41, v2
	v_mov_b32_e32 v50, v2
	v_mov_b32_e32 v51, v2
	v_mov_b32_e32 v52, v2
	v_mov_b32_e32 v53, v2
	v_mov_b32_e32 v54, v2
	v_mov_b32_e32 v55, v2
	v_mov_b32_e32 v56, v2
	v_mov_b32_e32 v57, v2
	v_mov_b32_e32 v10, v2
	v_mov_b32_e32 v11, v2
	v_mov_b32_e32 v12, v2
	v_mov_b32_e32 v13, v2
	v_mov_b32_e32 v14, v2
	v_mov_b32_e32 v15, v2
	v_mov_b32_e32 v16, v2
	v_mov_b32_e32 v17, v2
	v_mov_b32_e32 v26, v2
	v_mov_b32_e32 v27, v2
	v_mov_b32_e32 v28, v2
	v_mov_b32_e32 v29, v2
	v_mov_b32_e32 v30, v2
	v_mov_b32_e32 v31, v2
	v_mov_b32_e32 v32, v2
	v_mov_b32_e32 v33, v2
	v_mov_b32_e32 v42, v2
	v_mov_b32_e32 v43, v2
	v_mov_b32_e32 v44, v2
	v_mov_b32_e32 v45, v2
	v_mov_b32_e32 v46, v2
	v_mov_b32_e32 v47, v2
	v_mov_b32_e32 v48, v2
	v_mov_b32_e32 v49, v2
	v_mov_b32_e32 v58, v2
	v_mov_b32_e32 v59, v2
	v_mov_b32_e32 v60, v2
	v_mov_b32_e32 v61, v2
	v_mov_b32_e32 v62, v2
	v_mov_b32_e32 v63, v2
	v_mov_b32_e32 v64, v2
	v_mov_b32_e32 v65, v2
	v_mov_b32_e32 v66, v2
	v_mov_b32_e32 v67, v2
	v_mov_b32_e32 v68, v2
	v_mov_b32_e32 v69, v2
	v_mov_b32_e32 v70, v2
	v_mov_b32_e32 v71, v2
	v_mov_b32_e32 v72, v2
	v_mov_b32_e32 v73, v2
	v_mov_b32_e32 v82, v2
	v_mov_b32_e32 v83, v2
	v_mov_b32_e32 v84, v2
	v_mov_b32_e32 v85, v2
	v_mov_b32_e32 v86, v2
	v_mov_b32_e32 v87, v2
	v_mov_b32_e32 v88, v2
	v_mov_b32_e32 v89, v2
	v_mov_b32_e32 v98, v2
	v_mov_b32_e32 v99, v2
	v_mov_b32_e32 v100, v2
	v_mov_b32_e32 v101, v2
	v_mov_b32_e32 v102, v2
	v_mov_b32_e32 v103, v2
	v_mov_b32_e32 v104, v2
	v_mov_b32_e32 v105, v2
	v_mov_b32_e32 v114, v2
	v_mov_b32_e32 v115, v2
	v_mov_b32_e32 v116, v2
	v_mov_b32_e32 v117, v2
	v_mov_b32_e32 v118, v2
	v_mov_b32_e32 v119, v2
	v_mov_b32_e32 v120, v2
	v_mov_b32_e32 v121, v2
	v_mov_b32_e32 v74, v2
	v_mov_b32_e32 v75, v2
	v_mov_b32_e32 v76, v2
	v_mov_b32_e32 v77, v2
	v_mov_b32_e32 v78, v2
	v_mov_b32_e32 v79, v2
	v_mov_b32_e32 v80, v2
	v_mov_b32_e32 v81, v2
	v_mov_b32_e32 v90, v2
	v_mov_b32_e32 v91, v2
	v_mov_b32_e32 v92, v2
	v_mov_b32_e32 v93, v2
	v_mov_b32_e32 v94, v2
	v_mov_b32_e32 v95, v2
	v_mov_b32_e32 v96, v2
	v_mov_b32_e32 v97, v2
	v_mov_b32_e32 v106, v2
	v_mov_b32_e32 v107, v2
	v_mov_b32_e32 v108, v2
	v_mov_b32_e32 v109, v2
	v_mov_b32_e32 v110, v2
	v_mov_b32_e32 v111, v2
	v_mov_b32_e32 v112, v2
	v_mov_b32_e32 v113, v2
	v_mov_b32_e32 v126, v2
	v_mov_b32_e32 v127, v2
	v_mov_b32_e32 v128, v2
	v_mov_b32_e32 v129, v2
	v_mov_b32_e32 v138, v2
	v_mov_b32_e32 v139, v2
	v_mov_b32_e32 v140, v2
	v_mov_b32_e32 v141, v2
	s_branch .LBB0_215

.LBB0_353:
	ds_read_b128 v[136:139], v153
	ds_read_b128 v[140:143], v153 offset:1024
	ds_read_b128 v[158:161], v153 offset:2048
	ds_read_b128 v[162:165], v153 offset:3072
	ds_read_b128 v[166:169], v154
	ds_read_b128 v[170:173], v154 offset:1024
	ds_read_b128 v[174:177], v154 offset:2048
	ds_read_b128 v[178:181], v154 offset:3072
	s_add_i32 s66, s63, 0xfffe0080
	s_cmp_eq_u32 s65, 4
	s_cselect_b32 s68, s1, s66
	s_cselect_b32 s67, s62, s64
	s_or_b32 s66, s68, 0x80
	s_mov_b32 m0, s48
	s_nop 0
	buffer_load_dwordx4 v147, s[12:15], s63 offen lds
	s_nop 0
	s_mov_b32 m0, s49
	s_nop 0
	buffer_load_dwordx4 v148, s[12:15], s63 offen lds
	ds_read_b128 v[182:185], v155
	ds_read_b128 v[186:189], v155 offset:1024
	ds_read_b128 v[190:193], v155 offset:2048
	ds_read_b128 v[194:197], v155 offset:3072
	ds_read_b128 v[198:201], v155 offset:4096
	ds_read_b128 v[202:205], v155 offset:5120
	ds_read_b128 v[206:209], v155 offset:6144
	ds_read_b128 v[210:213], v155 offset:7168
	s_waitcnt vmcnt(8)
	s_waitcnt lgkmcnt(0)
	s_barrier
	s_setprio 1
	s_waitcnt lgkmcnt(0)
	v_mfma_i32_16x16x64_i8 v[126:129], v[136:139], v[182:185], v[126:129]
	v_mfma_i32_16x16x64_i8 v[122:125], v[158:161], v[182:185], v[122:125]
	v_mfma_i32_16x16x64_i8 v[118:121], v[136:139], v[190:193], v[118:121]
	v_mfma_i32_16x16x64_i8 v[114:117], v[158:161], v[190:193], v[114:117]
	v_mfma_i32_16x16x64_i8 v[110:113], v[136:139], v[198:201], v[110:113]
	v_mfma_i32_16x16x64_i8 v[106:109], v[158:161], v[198:201], v[106:109]
	v_mfma_i32_16x16x64_i8 v[102:105], v[136:139], v[206:209], v[102:105]
	v_mfma_i32_16x16x64_i8 v[98:101], v[158:161], v[206:209], v[98:101]
	v_mfma_i32_16x16x64_i8 v[126:129], v[140:143], v[186:189], v[126:129]
	v_mfma_i32_16x16x64_i8 v[122:125], v[162:165], v[186:189], v[122:125]
	v_mfma_i32_16x16x64_i8 v[118:121], v[140:143], v[194:197], v[118:121]
	v_mfma_i32_16x16x64_i8 v[114:117], v[162:165], v[194:197], v[114:117]
	v_mfma_i32_16x16x64_i8 v[110:113], v[140:143], v[202:205], v[110:113]
	v_mfma_i32_16x16x64_i8 v[106:109], v[162:165], v[202:205], v[106:109]
	v_mfma_i32_16x16x64_i8 v[102:105], v[140:143], v[210:213], v[102:105]
	v_mfma_i32_16x16x64_i8 v[98:101], v[162:165], v[210:213], v[98:101]
	v_mfma_i32_16x16x64_i8 v[94:97], v[166:169], v[182:185], v[94:97]
	v_mfma_i32_16x16x64_i8 v[90:93], v[174:177], v[182:185], v[90:93]
	v_mfma_i32_16x16x64_i8 v[86:89], v[166:169], v[190:193], v[86:89]
	v_mfma_i32_16x16x64_i8 v[82:85], v[174:177], v[190:193], v[82:85]
	v_mfma_i32_16x16x64_i8 v[78:81], v[166:169], v[198:201], v[78:81]
	v_mfma_i32_16x16x64_i8 v[74:77], v[174:177], v[198:201], v[74:77]
	v_mfma_i32_16x16x64_i8 v[70:73], v[166:169], v[206:209], v[70:73]
	v_mfma_i32_16x16x64_i8 v[66:69], v[174:177], v[206:209], v[66:69]
	v_mfma_i32_16x16x64_i8 v[94:97], v[170:173], v[186:189], v[94:97]
	v_mfma_i32_16x16x64_i8 v[90:93], v[178:181], v[186:189], v[90:93]
	v_mfma_i32_16x16x64_i8 v[86:89], v[170:173], v[194:197], v[86:89]
	v_mfma_i32_16x16x64_i8 v[82:85], v[178:181], v[194:197], v[82:85]
	v_mfma_i32_16x16x64_i8 v[78:81], v[170:173], v[202:205], v[78:81]
	v_mfma_i32_16x16x64_i8 v[74:77], v[178:181], v[202:205], v[74:77]
	v_mfma_i32_16x16x64_i8 v[70:73], v[170:173], v[210:213], v[70:73]
	v_mfma_i32_16x16x64_i8 v[66:69], v[178:181], v[210:213], v[66:69]
	s_setprio 0
	s_barrier
	ds_read_b128 v[182:185], v155 offset:16384
	ds_read_b128 v[186:189], v155 offset:17408
	s_mov_b32 m0, s34
	s_nop 0
	buffer_load_dwordx4 v145, s[8:11], s67 offen lds
	ds_read_b128 v[190:193], v155 offset:18432
	ds_read_b128 v[194:197], v155 offset:19456
	s_add_i32 s69, s67, 0x20000
	s_mov_b32 m0, s35
	s_nop 0
	buffer_load_dwordx4 v146, s[8:11], s67 offen lds
	ds_read_b128 v[198:201], v155 offset:20480
	ds_read_b128 v[202:205], v155 offset:21504
	s_nop 0
	s_mov_b32 m0, s36
	s_nop 0
	buffer_load_dwordx4 v145, s[8:11], s69 offen lds
	ds_read_b128 v[206:209], v155 offset:22528
	ds_read_b128 v[210:213], v155 offset:23552
	s_nop 0
	s_mov_b32 m0, s37
	s_nop 0
	buffer_load_dwordx4 v146, s[8:11], s69 offen lds
	s_nop 0
	s_mov_b32 m0, s33
	s_nop 0
	buffer_load_dwordx4 v147, s[12:15], s68 offen lds
	s_nop 0
	s_mov_b32 m0, s2
	s_nop 0
	buffer_load_dwordx4 v148, s[12:15], s68 offen lds
	s_waitcnt vmcnt(8)
	s_waitcnt lgkmcnt(0)
	s_barrier
	s_setprio 1
	s_waitcnt lgkmcnt(0)
	v_mfma_i32_16x16x64_i8 v[62:65], v[136:139], v[182:185], v[62:65]
	v_mfma_i32_16x16x64_i8 v[58:61], v[158:161], v[182:185], v[58:61]
	v_mfma_i32_16x16x64_i8 v[54:57], v[136:139], v[190:193], v[54:57]
	v_mfma_i32_16x16x64_i8 v[50:53], v[158:161], v[190:193], v[50:53]
	v_mfma_i32_16x16x64_i8 v[46:49], v[136:139], v[198:201], v[46:49]
	v_mfma_i32_16x16x64_i8 v[42:45], v[158:161], v[198:201], v[42:45]
	v_mfma_i32_16x16x64_i8 v[38:41], v[136:139], v[206:209], v[38:41]
	v_mfma_i32_16x16x64_i8 v[34:37], v[158:161], v[206:209], v[34:37]
	v_mfma_i32_16x16x64_i8 v[62:65], v[140:143], v[186:189], v[62:65]
	v_mfma_i32_16x16x64_i8 v[58:61], v[162:165], v[186:189], v[58:61]
	v_mfma_i32_16x16x64_i8 v[54:57], v[140:143], v[194:197], v[54:57]
	v_mfma_i32_16x16x64_i8 v[50:53], v[162:165], v[194:197], v[50:53]
	v_mfma_i32_16x16x64_i8 v[46:49], v[140:143], v[202:205], v[46:49]
	v_mfma_i32_16x16x64_i8 v[42:45], v[162:165], v[202:205], v[42:45]
	v_mfma_i32_16x16x64_i8 v[38:41], v[140:143], v[210:213], v[38:41]
	v_mfma_i32_16x16x64_i8 v[34:37], v[162:165], v[210:213], v[34:37]
	v_mfma_i32_16x16x64_i8 v[30:33], v[166:169], v[182:185], v[30:33]
	v_mfma_i32_16x16x64_i8 v[26:29], v[174:177], v[182:185], v[26:29]
	v_mfma_i32_16x16x64_i8 v[22:25], v[166:169], v[190:193], v[22:25]
	v_mfma_i32_16x16x64_i8 v[18:21], v[174:177], v[190:193], v[18:21]
	v_mfma_i32_16x16x64_i8 v[14:17], v[166:169], v[198:201], v[14:17]
	v_mfma_i32_16x16x64_i8 v[10:13], v[174:177], v[198:201], v[10:13]
	v_mfma_i32_16x16x64_i8 v[6:9], v[166:169], v[206:209], v[6:9]
	v_mfma_i32_16x16x64_i8 v[2:5], v[174:177], v[206:209], v[2:5]
	v_mfma_i32_16x16x64_i8 v[30:33], v[170:173], v[186:189], v[30:33]
	v_mfma_i32_16x16x64_i8 v[26:29], v[178:181], v[186:189], v[26:29]
	v_mfma_i32_16x16x64_i8 v[22:25], v[170:173], v[194:197], v[22:25]
	v_mfma_i32_16x16x64_i8 v[18:21], v[178:181], v[194:197], v[18:21]
	v_mfma_i32_16x16x64_i8 v[14:17], v[170:173], v[202:205], v[14:17]
	v_mfma_i32_16x16x64_i8 v[10:13], v[178:181], v[202:205], v[10:13]
	v_mfma_i32_16x16x64_i8 v[6:9], v[170:173], v[210:213], v[6:9]
	v_mfma_i32_16x16x64_i8 v[2:5], v[178:181], v[210:213], v[2:5]
	s_setprio 0
	s_barrier
	ds_read_b128 v[136:139], v156
	ds_read_b128 v[140:143], v156 offset:1024
	ds_read_b128 v[158:161], v156 offset:2048
	ds_read_b128 v[162:165], v156 offset:3072
	ds_read_b128 v[166:169], v157
	ds_read_b128 v[170:173], v157 offset:1024
	ds_read_b128 v[174:177], v157 offset:2048
	ds_read_b128 v[178:181], v157 offset:3072
	s_add_i32 s68, s68, 0x20000
	s_mov_b32 m0, s3
	s_nop 0
	buffer_load_dwordx4 v147, s[12:15], s68 offen lds
	s_nop 0
	s_mov_b32 m0, s38
	s_nop 0
	buffer_load_dwordx4 v148, s[12:15], s68 offen lds
	ds_read_b128 v[182:185], v155 offset:32768
	ds_read_b128 v[186:189], v155 offset:33792
	ds_read_b128 v[190:193], v155 offset:34816
	ds_read_b128 v[194:197], v155 offset:35840
	ds_read_b128 v[198:201], v155 offset:36864
	ds_read_b128 v[202:205], v155 offset:37888
	ds_read_b128 v[206:209], v155 offset:38912
	ds_read_b128 v[210:213], v155 offset:39936
	s_waitcnt vmcnt(8)
	s_waitcnt lgkmcnt(0)
	s_barrier
	s_setprio 1
	s_waitcnt lgkmcnt(0)
	v_mfma_i32_16x16x64_i8 v[126:129], v[136:139], v[182:185], v[126:129]
	v_mfma_i32_16x16x64_i8 v[122:125], v[158:161], v[182:185], v[122:125]
	v_mfma_i32_16x16x64_i8 v[118:121], v[136:139], v[190:193], v[118:121]
	v_mfma_i32_16x16x64_i8 v[114:117], v[158:161], v[190:193], v[114:117]
	v_mfma_i32_16x16x64_i8 v[110:113], v[136:139], v[198:201], v[110:113]
	v_mfma_i32_16x16x64_i8 v[106:109], v[158:161], v[198:201], v[106:109]
	v_mfma_i32_16x16x64_i8 v[102:105], v[136:139], v[206:209], v[102:105]
	v_mfma_i32_16x16x64_i8 v[98:101], v[158:161], v[206:209], v[98:101]
	v_mfma_i32_16x16x64_i8 v[126:129], v[140:143], v[186:189], v[126:129]
	v_mfma_i32_16x16x64_i8 v[122:125], v[162:165], v[186:189], v[122:125]
	v_mfma_i32_16x16x64_i8 v[118:121], v[140:143], v[194:197], v[118:121]
	v_mfma_i32_16x16x64_i8 v[114:117], v[162:165], v[194:197], v[114:117]
	v_mfma_i32_16x16x64_i8 v[110:113], v[140:143], v[202:205], v[110:113]
	v_mfma_i32_16x16x64_i8 v[106:109], v[162:165], v[202:205], v[106:109]
	v_mfma_i32_16x16x64_i8 v[102:105], v[140:143], v[210:213], v[102:105]
	v_mfma_i32_16x16x64_i8 v[98:101], v[162:165], v[210:213], v[98:101]
	v_mfma_i32_16x16x64_i8 v[94:97], v[166:169], v[182:185], v[94:97]
	v_mfma_i32_16x16x64_i8 v[90:93], v[174:177], v[182:185], v[90:93]
	v_mfma_i32_16x16x64_i8 v[86:89], v[166:169], v[190:193], v[86:89]
	v_mfma_i32_16x16x64_i8 v[82:85], v[174:177], v[190:193], v[82:85]
	v_mfma_i32_16x16x64_i8 v[78:81], v[166:169], v[198:201], v[78:81]
	v_mfma_i32_16x16x64_i8 v[74:77], v[174:177], v[198:201], v[74:77]
	v_mfma_i32_16x16x64_i8 v[70:73], v[166:169], v[206:209], v[70:73]
	v_mfma_i32_16x16x64_i8 v[66:69], v[174:177], v[206:209], v[66:69]
	v_mfma_i32_16x16x64_i8 v[94:97], v[170:173], v[186:189], v[94:97]
	v_mfma_i32_16x16x64_i8 v[90:93], v[178:181], v[186:189], v[90:93]
	v_mfma_i32_16x16x64_i8 v[86:89], v[170:173], v[194:197], v[86:89]
	v_mfma_i32_16x16x64_i8 v[82:85], v[178:181], v[194:197], v[82:85]
	v_mfma_i32_16x16x64_i8 v[78:81], v[170:173], v[202:205], v[78:81]
	v_mfma_i32_16x16x64_i8 v[74:77], v[178:181], v[202:205], v[74:77]
	v_mfma_i32_16x16x64_i8 v[70:73], v[170:173], v[210:213], v[70:73]
	v_mfma_i32_16x16x64_i8 v[66:69], v[178:181], v[210:213], v[66:69]
	s_setprio 0
	s_barrier
	ds_read_b128 v[182:185], v155 offset:49152
	ds_read_b128 v[186:189], v155 offset:50176
	s_or_b32 s68, s67, 0x80
	s_mov_b32 m0, s41
	s_nop 0
	buffer_load_dwordx4 v145, s[8:11], s68 offen lds
	ds_read_b128 v[190:193], v155 offset:51200
	ds_read_b128 v[194:197], v155 offset:52224
	s_add_i32 s67, s67, 0x20080
	s_mov_b32 m0, s42
	s_nop 0
	buffer_load_dwordx4 v146, s[8:11], s68 offen lds
	ds_read_b128 v[198:201], v155 offset:53248
	ds_read_b128 v[202:205], v155 offset:54272
	s_nop 0
	s_mov_b32 m0, s45
	s_nop 0
	buffer_load_dwordx4 v145, s[8:11], s67 offen lds
	ds_read_b128 v[206:209], v155 offset:55296
	ds_read_b128 v[210:213], v155 offset:56320
	s_nop 0
	s_mov_b32 m0, s46
	s_nop 0
	buffer_load_dwordx4 v146, s[8:11], s67 offen lds
	s_nop 0
	s_mov_b32 m0, s43
	s_nop 0
	buffer_load_dwordx4 v147, s[12:15], s66 offen lds
	s_nop 0
	s_mov_b32 m0, s44
	s_nop 0
	buffer_load_dwordx4 v148, s[12:15], s66 offen lds
	s_waitcnt vmcnt(8)
	s_waitcnt lgkmcnt(0)
	s_barrier
	s_setprio 1
	s_waitcnt lgkmcnt(0)
	v_mfma_i32_16x16x64_i8 v[62:65], v[136:139], v[182:185], v[62:65]
	v_mfma_i32_16x16x64_i8 v[58:61], v[158:161], v[182:185], v[58:61]
	v_mfma_i32_16x16x64_i8 v[54:57], v[136:139], v[190:193], v[54:57]
	v_mfma_i32_16x16x64_i8 v[50:53], v[158:161], v[190:193], v[50:53]
	v_mfma_i32_16x16x64_i8 v[46:49], v[136:139], v[198:201], v[46:49]
	v_mfma_i32_16x16x64_i8 v[42:45], v[158:161], v[198:201], v[42:45]
	v_mfma_i32_16x16x64_i8 v[38:41], v[136:139], v[206:209], v[38:41]
	v_mfma_i32_16x16x64_i8 v[34:37], v[158:161], v[206:209], v[34:37]
	v_mfma_i32_16x16x64_i8 v[62:65], v[140:143], v[186:189], v[62:65]
	v_mfma_i32_16x16x64_i8 v[58:61], v[162:165], v[186:189], v[58:61]
	v_mfma_i32_16x16x64_i8 v[54:57], v[140:143], v[194:197], v[54:57]
	v_mfma_i32_16x16x64_i8 v[50:53], v[162:165], v[194:197], v[50:53]
	v_mfma_i32_16x16x64_i8 v[46:49], v[140:143], v[202:205], v[46:49]
	v_mfma_i32_16x16x64_i8 v[42:45], v[162:165], v[202:205], v[42:45]
	v_mfma_i32_16x16x64_i8 v[38:41], v[140:143], v[210:213], v[38:41]
	v_mfma_i32_16x16x64_i8 v[34:37], v[162:165], v[210:213], v[34:37]
	v_mfma_i32_16x16x64_i8 v[30:33], v[166:169], v[182:185], v[30:33]
	v_mfma_i32_16x16x64_i8 v[26:29], v[174:177], v[182:185], v[26:29]
	v_mfma_i32_16x16x64_i8 v[22:25], v[166:169], v[190:193], v[22:25]
	v_mfma_i32_16x16x64_i8 v[18:21], v[174:177], v[190:193], v[18:21]
	v_mfma_i32_16x16x64_i8 v[14:17], v[166:169], v[198:201], v[14:17]
	v_mfma_i32_16x16x64_i8 v[10:13], v[174:177], v[198:201], v[10:13]
	v_mfma_i32_16x16x64_i8 v[6:9], v[166:169], v[206:209], v[6:9]
	v_mfma_i32_16x16x64_i8 v[2:5], v[174:177], v[206:209], v[2:5]
	v_mfma_i32_16x16x64_i8 v[30:33], v[170:173], v[186:189], v[30:33]
	v_mfma_i32_16x16x64_i8 v[26:29], v[178:181], v[186:189], v[26:29]
	v_mfma_i32_16x16x64_i8 v[22:25], v[170:173], v[194:197], v[22:25]
	v_mfma_i32_16x16x64_i8 v[18:21], v[178:181], v[194:197], v[18:21]
	v_mfma_i32_16x16x64_i8 v[14:17], v[170:173], v[202:205], v[14:17]
	v_mfma_i32_16x16x64_i8 v[10:13], v[178:181], v[202:205], v[10:13]
	v_mfma_i32_16x16x64_i8 v[6:9], v[170:173], v[210:213], v[6:9]
	v_mfma_i32_16x16x64_i8 v[2:5], v[178:181], v[210:213], v[2:5]
	s_setprio 0
	s_barrier
	s_add_i32 s65, s65, 2
	s_addk_i32 s63, 0x100
	s_addk_i32 s64, 0x100
	s_cmp_gt_u32 s65, 5
	s_cbranch_scc0 .LBB0_353
	s_and_b64 vcc, exec, s[24:25]
	s_cbranch_vccz .LBB0_356
	s_barrier

.LBB0_467:
	v_add_u32_e32 v147, 0x10000, v132
	ds_read_b128 v[138:141], v147
	ds_read_b128 v[142:145], v147 offset:1024
	ds_read_b128 v[148:151], v147 offset:2048
	ds_read_b128 v[152:155], v147 offset:3072
	v_add_u32_e32 v147, 0x14000, v132
	ds_read_b128 v[156:159], v147
	ds_read_b128 v[160:163], v147 offset:1024
	ds_read_b128 v[164:167], v147 offset:2048
	ds_read_b128 v[168:171], v147 offset:3072
	s_add_i32 s59, s3, s1
	s_add_i32 s58, s33, s1
	s_add_i32 s55, s59, 0x1600
	s_addk_i32 s58, 0x1600
	s_cmp_eq_u32 s1, 0
	s_cselect_b32 s60, s53, s55
	s_cselect_b32 s58, s54, s58
	s_add_i32 s55, s60, 0x80
	s_add_i32 s59, s59, 0xb1580
	s_mov_b32 m0, s46
	s_nop 0
	buffer_load_dwordx4 v130, s[12:15], s59 offen lds
	s_nop 0
	s_mov_b32 m0, s47
	s_nop 0
	buffer_load_dwordx4 v131, s[12:15], s59 offen lds
	ds_read_b128 v[172:175], v133
	ds_read_b128 v[176:179], v133 offset:1024
	ds_read_b128 v[180:183], v133 offset:2048
	ds_read_b128 v[184:187], v133 offset:3072
	ds_read_b128 v[188:191], v133 offset:4096
	ds_read_b128 v[192:195], v133 offset:5120
	ds_read_b128 v[196:199], v133 offset:6144
	ds_read_b128 v[200:203], v133 offset:7168
	s_waitcnt vmcnt(8)
	s_waitcnt lgkmcnt(0)
	s_barrier
	s_setprio 1
	s_waitcnt lgkmcnt(7)
	v_mfma_f32_16x16x32_bf16 v[134:137], v[138:141], v[172:175], v[134:137]
	v_mfma_f32_16x16x32_bf16 v[122:125], v[148:151], v[172:175], v[122:125]
	s_waitcnt lgkmcnt(5)
	v_mfma_f32_16x16x32_bf16 v[110:113], v[138:141], v[180:183], v[110:113]
	v_mfma_f32_16x16x32_bf16 v[106:109], v[148:151], v[180:183], v[106:109]
	s_waitcnt lgkmcnt(3)
	v_mfma_f32_16x16x32_bf16 v[94:97], v[138:141], v[188:191], v[94:97]
	v_mfma_f32_16x16x32_bf16 v[90:93], v[148:151], v[188:191], v[90:93]
	s_waitcnt lgkmcnt(1)
	v_mfma_f32_16x16x32_bf16 v[78:81], v[138:141], v[196:199], v[78:81]
	v_mfma_f32_16x16x32_bf16 v[74:77], v[148:151], v[196:199], v[74:77]
	v_mfma_f32_16x16x32_bf16 v[134:137], v[142:145], v[176:179], v[134:137]
	v_mfma_f32_16x16x32_bf16 v[122:125], v[152:155], v[176:179], v[122:125]
	v_mfma_f32_16x16x32_bf16 v[110:113], v[142:145], v[184:187], v[110:113]
	v_mfma_f32_16x16x32_bf16 v[106:109], v[152:155], v[184:187], v[106:109]
	v_mfma_f32_16x16x32_bf16 v[94:97], v[142:145], v[192:195], v[94:97]
	v_mfma_f32_16x16x32_bf16 v[90:93], v[152:155], v[192:195], v[90:93]
	s_waitcnt lgkmcnt(0)
	v_mfma_f32_16x16x32_bf16 v[78:81], v[142:145], v[200:203], v[78:81]
	v_mfma_f32_16x16x32_bf16 v[74:77], v[152:155], v[200:203], v[74:77]
	v_mfma_f32_16x16x32_bf16 v[118:121], v[156:159], v[172:175], v[118:121]
	v_mfma_f32_16x16x32_bf16 v[114:117], v[164:167], v[172:175], v[114:117]
	v_mfma_f32_16x16x32_bf16 v[102:105], v[156:159], v[180:183], v[102:105]
	v_mfma_f32_16x16x32_bf16 v[98:101], v[164:167], v[180:183], v[98:101]
	v_mfma_f32_16x16x32_bf16 v[86:89], v[156:159], v[188:191], v[86:89]
	v_mfma_f32_16x16x32_bf16 v[82:85], v[164:167], v[188:191], v[82:85]
	v_mfma_f32_16x16x32_bf16 v[70:73], v[156:159], v[196:199], v[70:73]
	v_mfma_f32_16x16x32_bf16 v[66:69], v[164:167], v[196:199], v[66:69]
	v_mfma_f32_16x16x32_bf16 v[118:121], v[160:163], v[176:179], v[118:121]
	v_mfma_f32_16x16x32_bf16 v[114:117], v[168:171], v[176:179], v[114:117]
	v_mfma_f32_16x16x32_bf16 v[102:105], v[160:163], v[184:187], v[102:105]
	v_mfma_f32_16x16x32_bf16 v[98:101], v[168:171], v[184:187], v[98:101]
	v_mfma_f32_16x16x32_bf16 v[86:89], v[160:163], v[192:195], v[86:89]
	v_mfma_f32_16x16x32_bf16 v[82:85], v[168:171], v[192:195], v[82:85]
	v_mfma_f32_16x16x32_bf16 v[70:73], v[160:163], v[200:203], v[70:73]
	v_mfma_f32_16x16x32_bf16 v[66:69], v[168:171], v[200:203], v[66:69]
	s_setprio 0
	s_barrier
	ds_read_b128 v[172:175], v133 offset:16384
	ds_read_b128 v[176:179], v133 offset:17408
	s_mov_b32 m0, s29
	s_nop 0
	buffer_load_dwordx4 v130, s[8:11], s58 offen lds
	ds_read_b128 v[180:183], v133 offset:18432
	ds_read_b128 v[184:187], v133 offset:19456
	s_add_i32 s59, s58, 0xb0000
	s_mov_b32 m0, s34
	s_nop 0
	buffer_load_dwordx4 v131, s[8:11], s58 offen lds
	ds_read_b128 v[188:191], v133 offset:20480
	ds_read_b128 v[192:195], v133 offset:21504
	s_nop 0
	s_mov_b32 m0, s35
	s_nop 0
	buffer_load_dwordx4 v130, s[8:11], s59 offen lds
	ds_read_b128 v[196:199], v133 offset:22528
	ds_read_b128 v[200:203], v133 offset:23552
	s_nop 0
	s_mov_b32 m0, s36
	s_nop 0
	buffer_load_dwordx4 v131, s[8:11], s59 offen lds
	s_nop 0
	s_mov_b32 m0, s28
	s_nop 0
	buffer_load_dwordx4 v130, s[12:15], s60 offen lds
	s_nop 0
	s_mov_b32 m0, s37
	s_nop 0
	buffer_load_dwordx4 v131, s[12:15], s60 offen lds
	s_waitcnt vmcnt(8)
	s_waitcnt lgkmcnt(0)
	s_barrier
	s_setprio 1
	s_waitcnt lgkmcnt(7)
	v_mfma_f32_16x16x32_bf16 v[62:65], v[138:141], v[172:175], v[62:65]
	v_mfma_f32_16x16x32_bf16 v[58:61], v[148:151], v[172:175], v[58:61]
	s_waitcnt lgkmcnt(5)
	v_mfma_f32_16x16x32_bf16 v[46:49], v[138:141], v[180:183], v[46:49]
	v_mfma_f32_16x16x32_bf16 v[42:45], v[148:151], v[180:183], v[42:45]
	s_waitcnt lgkmcnt(3)
	v_mfma_f32_16x16x32_bf16 v[30:33], v[138:141], v[188:191], v[30:33]
	v_mfma_f32_16x16x32_bf16 v[26:29], v[148:151], v[188:191], v[26:29]
	s_waitcnt lgkmcnt(1)
	v_mfma_f32_16x16x32_bf16 v[14:17], v[138:141], v[196:199], v[14:17]
	v_mfma_f32_16x16x32_bf16 v[10:13], v[148:151], v[196:199], v[10:13]
	v_mfma_f32_16x16x32_bf16 v[62:65], v[142:145], v[176:179], v[62:65]
	v_mfma_f32_16x16x32_bf16 v[58:61], v[152:155], v[176:179], v[58:61]
	v_mfma_f32_16x16x32_bf16 v[46:49], v[142:145], v[184:187], v[46:49]
	v_mfma_f32_16x16x32_bf16 v[42:45], v[152:155], v[184:187], v[42:45]
	v_mfma_f32_16x16x32_bf16 v[30:33], v[142:145], v[192:195], v[30:33]
	v_mfma_f32_16x16x32_bf16 v[26:29], v[152:155], v[192:195], v[26:29]
	s_waitcnt lgkmcnt(0)
	v_mfma_f32_16x16x32_bf16 v[14:17], v[142:145], v[200:203], v[14:17]
	v_mfma_f32_16x16x32_bf16 v[10:13], v[152:155], v[200:203], v[10:13]
	v_mfma_f32_16x16x32_bf16 v[54:57], v[156:159], v[172:175], v[54:57]
	v_mfma_f32_16x16x32_bf16 v[50:53], v[164:167], v[172:175], v[50:53]
	v_mfma_f32_16x16x32_bf16 v[38:41], v[156:159], v[180:183], v[38:41]
	v_mfma_f32_16x16x32_bf16 v[34:37], v[164:167], v[180:183], v[34:37]
	v_mfma_f32_16x16x32_bf16 v[22:25], v[156:159], v[188:191], v[22:25]
	v_mfma_f32_16x16x32_bf16 v[18:21], v[164:167], v[188:191], v[18:21]
	v_mfma_f32_16x16x32_bf16 v[6:9], v[156:159], v[196:199], v[6:9]
	v_mfma_f32_16x16x32_bf16 v[2:5], v[164:167], v[196:199], v[2:5]
	v_mfma_f32_16x16x32_bf16 v[54:57], v[160:163], v[176:179], v[54:57]
	v_mfma_f32_16x16x32_bf16 v[50:53], v[168:171], v[176:179], v[50:53]
	v_mfma_f32_16x16x32_bf16 v[38:41], v[160:163], v[184:187], v[38:41]
	v_mfma_f32_16x16x32_bf16 v[34:37], v[168:171], v[184:187], v[34:37]
	v_mfma_f32_16x16x32_bf16 v[22:25], v[160:163], v[192:195], v[22:25]
	v_mfma_f32_16x16x32_bf16 v[18:21], v[168:171], v[192:195], v[18:21]
	v_mfma_f32_16x16x32_bf16 v[6:9], v[160:163], v[200:203], v[6:9]
	v_mfma_f32_16x16x32_bf16 v[2:5], v[168:171], v[200:203], v[2:5]
	s_setprio 0
	s_barrier
	v_add_u32_e32 v147, 0x18000, v132
	ds_read_b128 v[138:141], v147
	ds_read_b128 v[142:145], v147 offset:1024
	ds_read_b128 v[148:151], v147 offset:2048
	ds_read_b128 v[152:155], v147 offset:3072
	v_add_u32_e32 v147, 0x1c000, v132
	ds_read_b128 v[156:159], v147
	ds_read_b128 v[160:163], v147 offset:1024
	ds_read_b128 v[164:167], v147 offset:2048
	ds_read_b128 v[168:171], v147 offset:3072
	s_add_i32 s59, s60, 0xb0000
	s_mov_b32 m0, s38
	s_nop 0
	buffer_load_dwordx4 v130, s[12:15], s59 offen lds
	s_nop 0
	s_mov_b32 m0, s39
	s_nop 0
	buffer_load_dwordx4 v131, s[12:15], s59 offen lds
	ds_read_b128 v[172:175], v133 offset:32768
	ds_read_b128 v[176:179], v133 offset:33792
	ds_read_b128 v[180:183], v133 offset:34816
	ds_read_b128 v[184:187], v133 offset:35840
	ds_read_b128 v[188:191], v133 offset:36864
	ds_read_b128 v[192:195], v133 offset:37888
	ds_read_b128 v[196:199], v133 offset:38912
	ds_read_b128 v[200:203], v133 offset:39936
	s_waitcnt vmcnt(8)
	s_waitcnt lgkmcnt(0)
	s_barrier
	s_setprio 1
	s_waitcnt lgkmcnt(7)
	v_mfma_f32_16x16x32_bf16 v[134:137], v[138:141], v[172:175], v[134:137]
	v_mfma_f32_16x16x32_bf16 v[122:125], v[148:151], v[172:175], v[122:125]
	s_waitcnt lgkmcnt(5)
	v_mfma_f32_16x16x32_bf16 v[110:113], v[138:141], v[180:183], v[110:113]
	v_mfma_f32_16x16x32_bf16 v[106:109], v[148:151], v[180:183], v[106:109]
	s_waitcnt lgkmcnt(3)
	v_mfma_f32_16x16x32_bf16 v[94:97], v[138:141], v[188:191], v[94:97]
	v_mfma_f32_16x16x32_bf16 v[90:93], v[148:151], v[188:191], v[90:93]
	s_waitcnt lgkmcnt(1)
	v_mfma_f32_16x16x32_bf16 v[78:81], v[138:141], v[196:199], v[78:81]
	v_mfma_f32_16x16x32_bf16 v[74:77], v[148:151], v[196:199], v[74:77]
	v_mfma_f32_16x16x32_bf16 v[134:137], v[142:145], v[176:179], v[134:137]
	v_mfma_f32_16x16x32_bf16 v[122:125], v[152:155], v[176:179], v[122:125]
	v_mfma_f32_16x16x32_bf16 v[110:113], v[142:145], v[184:187], v[110:113]
	v_mfma_f32_16x16x32_bf16 v[106:109], v[152:155], v[184:187], v[106:109]
	v_mfma_f32_16x16x32_bf16 v[94:97], v[142:145], v[192:195], v[94:97]
	v_mfma_f32_16x16x32_bf16 v[90:93], v[152:155], v[192:195], v[90:93]
	s_waitcnt lgkmcnt(0)
	v_mfma_f32_16x16x32_bf16 v[78:81], v[142:145], v[200:203], v[78:81]
	v_mfma_f32_16x16x32_bf16 v[74:77], v[152:155], v[200:203], v[74:77]
	v_mfma_f32_16x16x32_bf16 v[118:121], v[156:159], v[172:175], v[118:121]
	v_mfma_f32_16x16x32_bf16 v[114:117], v[164:167], v[172:175], v[114:117]
	v_mfma_f32_16x16x32_bf16 v[102:105], v[156:159], v[180:183], v[102:105]
	v_mfma_f32_16x16x32_bf16 v[98:101], v[164:167], v[180:183], v[98:101]
	v_mfma_f32_16x16x32_bf16 v[86:89], v[156:159], v[188:191], v[86:89]
	v_mfma_f32_16x16x32_bf16 v[82:85], v[164:167], v[188:191], v[82:85]
	v_mfma_f32_16x16x32_bf16 v[70:73], v[156:159], v[196:199], v[70:73]
	v_mfma_f32_16x16x32_bf16 v[66:69], v[164:167], v[196:199], v[66:69]
	v_mfma_f32_16x16x32_bf16 v[118:121], v[160:163], v[176:179], v[118:121]
	v_mfma_f32_16x16x32_bf16 v[114:117], v[168:171], v[176:179], v[114:117]
	v_mfma_f32_16x16x32_bf16 v[102:105], v[160:163], v[184:187], v[102:105]
	v_mfma_f32_16x16x32_bf16 v[98:101], v[168:171], v[184:187], v[98:101]
	v_mfma_f32_16x16x32_bf16 v[86:89], v[160:163], v[192:195], v[86:89]
	v_mfma_f32_16x16x32_bf16 v[82:85], v[168:171], v[192:195], v[82:85]
	v_mfma_f32_16x16x32_bf16 v[70:73], v[160:163], v[200:203], v[70:73]
	v_mfma_f32_16x16x32_bf16 v[66:69], v[168:171], v[200:203], v[66:69]
	s_setprio 0
	s_barrier
	ds_read_b128 v[172:175], v133 offset:49152
	ds_read_b128 v[176:179], v133 offset:50176
	s_add_i32 s59, s58, 0x80
	s_mov_b32 m0, s40
	s_nop 0
	buffer_load_dwordx4 v130, s[8:11], s59 offen lds
	ds_read_b128 v[180:183], v133 offset:51200
	ds_read_b128 v[184:187], v133 offset:52224
	s_add_i32 s58, s58, 0xb0080
	s_mov_b32 m0, s41
	s_nop 0
	buffer_load_dwordx4 v131, s[8:11], s59 offen lds
	ds_read_b128 v[188:191], v133 offset:53248
	ds_read_b128 v[192:195], v133 offset:54272
	s_nop 0
	s_mov_b32 m0, s44
	s_nop 0
	buffer_load_dwordx4 v130, s[8:11], s58 offen lds
	ds_read_b128 v[196:199], v133 offset:55296
	ds_read_b128 v[200:203], v133 offset:56320
	s_nop 0
	s_mov_b32 m0, s45
	s_nop 0
	buffer_load_dwordx4 v131, s[8:11], s58 offen lds
	s_nop 0
	s_mov_b32 m0, s42
	s_nop 0
	buffer_load_dwordx4 v130, s[12:15], s55 offen lds
	s_nop 0
	s_mov_b32 m0, s43
	s_nop 0
	buffer_load_dwordx4 v131, s[12:15], s55 offen lds
	s_waitcnt vmcnt(8)
	s_waitcnt lgkmcnt(0)
	s_barrier
	s_setprio 1
	s_waitcnt lgkmcnt(7)
	v_mfma_f32_16x16x32_bf16 v[62:65], v[138:141], v[172:175], v[62:65]
	v_mfma_f32_16x16x32_bf16 v[58:61], v[148:151], v[172:175], v[58:61]
	s_waitcnt lgkmcnt(5)
	v_mfma_f32_16x16x32_bf16 v[46:49], v[138:141], v[180:183], v[46:49]
	v_mfma_f32_16x16x32_bf16 v[42:45], v[148:151], v[180:183], v[42:45]
	s_waitcnt lgkmcnt(3)
	v_mfma_f32_16x16x32_bf16 v[30:33], v[138:141], v[188:191], v[30:33]
	v_mfma_f32_16x16x32_bf16 v[26:29], v[148:151], v[188:191], v[26:29]
	s_waitcnt lgkmcnt(1)
	v_mfma_f32_16x16x32_bf16 v[14:17], v[138:141], v[196:199], v[14:17]
	v_mfma_f32_16x16x32_bf16 v[10:13], v[148:151], v[196:199], v[10:13]
	v_mfma_f32_16x16x32_bf16 v[62:65], v[142:145], v[176:179], v[62:65]
	v_mfma_f32_16x16x32_bf16 v[58:61], v[152:155], v[176:179], v[58:61]
	v_mfma_f32_16x16x32_bf16 v[46:49], v[142:145], v[184:187], v[46:49]
	v_mfma_f32_16x16x32_bf16 v[42:45], v[152:155], v[184:187], v[42:45]
	v_mfma_f32_16x16x32_bf16 v[30:33], v[142:145], v[192:195], v[30:33]
	v_mfma_f32_16x16x32_bf16 v[26:29], v[152:155], v[192:195], v[26:29]
	s_waitcnt lgkmcnt(0)
	v_mfma_f32_16x16x32_bf16 v[14:17], v[142:145], v[200:203], v[14:17]
	v_mfma_f32_16x16x32_bf16 v[10:13], v[152:155], v[200:203], v[10:13]
	v_mfma_f32_16x16x32_bf16 v[54:57], v[156:159], v[172:175], v[54:57]
	v_mfma_f32_16x16x32_bf16 v[50:53], v[164:167], v[172:175], v[50:53]
	v_mfma_f32_16x16x32_bf16 v[38:41], v[156:159], v[180:183], v[38:41]
	v_mfma_f32_16x16x32_bf16 v[34:37], v[164:167], v[180:183], v[34:37]
	v_mfma_f32_16x16x32_bf16 v[22:25], v[156:159], v[188:191], v[22:25]
	v_mfma_f32_16x16x32_bf16 v[18:21], v[164:167], v[188:191], v[18:21]
	v_mfma_f32_16x16x32_bf16 v[6:9], v[156:159], v[196:199], v[6:9]
	v_mfma_f32_16x16x32_bf16 v[2:5], v[164:167], v[196:199], v[2:5]
	v_mfma_f32_16x16x32_bf16 v[54:57], v[160:163], v[176:179], v[54:57]
	v_mfma_f32_16x16x32_bf16 v[50:53], v[168:171], v[176:179], v[50:53]
	v_mfma_f32_16x16x32_bf16 v[38:41], v[160:163], v[184:187], v[38:41]
	v_mfma_f32_16x16x32_bf16 v[34:37], v[168:171], v[184:187], v[34:37]
	v_mfma_f32_16x16x32_bf16 v[22:25], v[160:163], v[192:195], v[22:25]
	v_mfma_f32_16x16x32_bf16 v[18:21], v[168:171], v[192:195], v[18:21]
	v_mfma_f32_16x16x32_bf16 v[6:9], v[160:163], v[200:203], v[6:9]
	v_mfma_f32_16x16x32_bf16 v[2:5], v[168:171], v[200:203], v[2:5]
	s_setprio 0
	s_barrier
	s_add_i32 s0, s0, 2
	s_addk_i32 s1, 0x100
	s_cmp_gt_u32 s0, 41
	s_cbranch_scc0 .LBB0_467
	s_andn2_b64 vcc, exec, s[6:7]
	s_cbranch_vccnz .LBB0_455
	v_mov_b32_e32 v2, 0
	s_mov_b32 s18, s50
	s_mov_b32 s31, s51
	s_mov_b32 s33, s54
	s_mov_b32 s3, s53
	s_mov_b32 s49, s52
	v_mov_b32_e32 v3, v2
	v_mov_b32_e32 v4, v2
	v_mov_b32_e32 v5, v2
	v_mov_b32_e32 v6, v2
	v_mov_b32_e32 v7, v2
	v_mov_b32_e32 v8, v2
	v_mov_b32_e32 v9, v2
	v_mov_b32_e32 v18, v2
	v_mov_b32_e32 v19, v2
	v_mov_b32_e32 v20, v2
	v_mov_b32_e32 v21, v2
	v_mov_b32_e32 v22, v2
	v_mov_b32_e32 v23, v2
	v_mov_b32_e32 v24, v2
	v_mov_b32_e32 v25, v2
	v_mov_b32_e32 v34, v2
	v_mov_b32_e32 v35, v2
	v_mov_b32_e32 v36, v2
	v_mov_b32_e32 v37, v2
	v_mov_b32_e32 v38, v2
	v_mov_b32_e32 v39, v2
	v_mov_b32_e32 v40, v2
	v_mov_b32_e32 v41, v2
	v_mov_b32_e32 v50, v2
	v_mov_b32_e32 v51, v2
	v_mov_b32_e32 v52, v2
	v_mov_b32_e32 v53, v2
	v_mov_b32_e32 v54, v2
	v_mov_b32_e32 v55, v2
	v_mov_b32_e32 v56, v2
	v_mov_b32_e32 v57, v2
	v_mov_b32_e32 v10, v2
	v_mov_b32_e32 v11, v2
	v_mov_b32_e32 v12, v2
	v_mov_b32_e32 v13, v2
	v_mov_b32_e32 v14, v2
	v_mov_b32_e32 v15, v2
	v_mov_b32_e32 v16, v2
	v_mov_b32_e32 v17, v2
	v_mov_b32_e32 v26, v2
	v_mov_b32_e32 v27, v2
	v_mov_b32_e32 v28, v2
	v_mov_b32_e32 v29, v2
	v_mov_b32_e32 v30, v2
	v_mov_b32_e32 v31, v2
	v_mov_b32_e32 v32, v2
	v_mov_b32_e32 v33, v2
	v_mov_b32_e32 v42, v2
	v_mov_b32_e32 v43, v2
	v_mov_b32_e32 v44, v2
	v_mov_b32_e32 v45, v2
	v_mov_b32_e32 v46, v2
	v_mov_b32_e32 v47, v2
	v_mov_b32_e32 v48, v2
	v_mov_b32_e32 v49, v2
	v_mov_b32_e32 v58, v2
	v_mov_b32_e32 v59, v2
	v_mov_b32_e32 v60, v2
	v_mov_b32_e32 v61, v2
	v_mov_b32_e32 v62, v2
	v_mov_b32_e32 v63, v2
	v_mov_b32_e32 v64, v2
	v_mov_b32_e32 v65, v2
	v_mov_b32_e32 v66, v2
	v_mov_b32_e32 v67, v2
	v_mov_b32_e32 v68, v2
	v_mov_b32_e32 v69, v2
	v_mov_b32_e32 v70, v2
	v_mov_b32_e32 v71, v2
	v_mov_b32_e32 v72, v2
	v_mov_b32_e32 v73, v2
	v_mov_b32_e32 v82, v2
	v_mov_b32_e32 v83, v2
	v_mov_b32_e32 v84, v2
	v_mov_b32_e32 v85, v2
	v_mov_b32_e32 v86, v2
	v_mov_b32_e32 v87, v2
	v_mov_b32_e32 v88, v2
	v_mov_b32_e32 v89, v2
	v_mov_b32_e32 v98, v2
	v_mov_b32_e32 v99, v2
	v_mov_b32_e32 v100, v2
	v_mov_b32_e32 v101, v2
	v_mov_b32_e32 v102, v2
	v_mov_b32_e32 v103, v2
	v_mov_b32_e32 v104, v2
	v_mov_b32_e32 v105, v2
	v_mov_b32_e32 v114, v2
	v_mov_b32_e32 v115, v2
	v_mov_b32_e32 v116, v2
	v_mov_b32_e32 v117, v2
	v_mov_b32_e32 v118, v2
	v_mov_b32_e32 v119, v2
	v_mov_b32_e32 v120, v2
	v_mov_b32_e32 v121, v2
	v_mov_b32_e32 v74, v2
	v_mov_b32_e32 v75, v2
	v_mov_b32_e32 v76, v2
	v_mov_b32_e32 v77, v2
	v_mov_b32_e32 v78, v2
	v_mov_b32_e32 v79, v2
	v_mov_b32_e32 v80, v2
	v_mov_b32_e32 v81, v2
	v_mov_b32_e32 v90, v2
	v_mov_b32_e32 v91, v2
	v_mov_b32_e32 v92, v2
	v_mov_b32_e32 v93, v2
	v_mov_b32_e32 v94, v2
	v_mov_b32_e32 v95, v2
	v_mov_b32_e32 v96, v2
	v_mov_b32_e32 v97, v2
	v_mov_b32_e32 v106, v2
	v_mov_b32_e32 v107, v2
	v_mov_b32_e32 v108, v2
	v_mov_b32_e32 v109, v2
	v_mov_b32_e32 v110, v2
	v_mov_b32_e32 v111, v2
	v_mov_b32_e32 v112, v2
	v_mov_b32_e32 v113, v2
	v_mov_b32_e32 v122, v2
	v_mov_b32_e32 v123, v2
	v_mov_b32_e32 v124, v2
	v_mov_b32_e32 v125, v2
	v_mov_b32_e32 v134, v2
	v_mov_b32_e32 v135, v2
	v_mov_b32_e32 v136, v2
	v_mov_b32_e32 v137, v2
	s_branch .LBB0_455

.LBB0_619:
	ds_read_b128 v[38:41], v210
	ds_read_b128 v[42:45], v210 offset:1024
	ds_read_b128 v[46:49], v210 offset:2048
	ds_read_b128 v[58:61], v210 offset:3072
	ds_read_b128 v[142:145], v211
	ds_read_b128 v[146:149], v211 offset:1024
	ds_read_b128 v[150:153], v211 offset:2048
	ds_read_b128 v[154:157], v211 offset:3072
	s_add_i32 s6, s1, 0xfffe0080
	s_cmp_eq_u32 s3, 4
	s_cselect_b32 s8, s75, s6
	s_cselect_b32 s7, s0, s2
	s_add_i32 s6, s8, 0x80
	s_mov_b32 m0, s68
	s_nop 0
	buffer_load_dwordx4 v206, s[16:19], s1 offen lds
	s_nop 0
	s_mov_b32 m0, s69
	s_nop 0
	buffer_load_dwordx4 v207, s[16:19], s1 offen lds
	ds_read_b128 v[166:169], v212
	ds_read_b128 v[170:173], v212 offset:1024
	ds_read_b128 v[174:177], v212 offset:2048
	ds_read_b128 v[178:181], v212 offset:3072
	ds_read_b128 v[190:193], v212 offset:4096
	ds_read_b128 v[194:197], v212 offset:5120
	ds_read_b128 v[198:201], v212 offset:6144
	ds_read_b128 v[216:219], v212 offset:7168
	s_waitcnt vmcnt(8)
	s_waitcnt lgkmcnt(0)
	s_barrier
	s_setprio 1
	s_waitcnt lgkmcnt(7)
	v_mfma_i32_16x16x64_i8 v[162:165], v[38:41], v[166:169], v[162:165]
	v_mfma_i32_16x16x64_i8 v[158:161], v[46:49], v[166:169], v[158:161]
	s_waitcnt lgkmcnt(5)
	v_mfma_i32_16x16x64_i8 v[130:133], v[38:41], v[174:177], v[130:133]
	v_mfma_i32_16x16x64_i8 v[126:129], v[46:49], v[174:177], v[126:129]
	s_waitcnt lgkmcnt(3)
	v_mfma_i32_16x16x64_i8 v[114:117], v[38:41], v[190:193], v[114:117]
	v_mfma_i32_16x16x64_i8 v[110:113], v[46:49], v[190:193], v[110:113]
	s_waitcnt lgkmcnt(1)
	v_mfma_i32_16x16x64_i8 v[98:101], v[38:41], v[198:201], v[98:101]
	v_mfma_i32_16x16x64_i8 v[94:97], v[46:49], v[198:201], v[94:97]
	v_mfma_i32_16x16x64_i8 v[162:165], v[42:45], v[170:173], v[162:165]
	v_mfma_i32_16x16x64_i8 v[158:161], v[58:61], v[170:173], v[158:161]
	v_mfma_i32_16x16x64_i8 v[130:133], v[42:45], v[178:181], v[130:133]
	v_mfma_i32_16x16x64_i8 v[126:129], v[58:61], v[178:181], v[126:129]
	v_mfma_i32_16x16x64_i8 v[114:117], v[42:45], v[194:197], v[114:117]
	v_mfma_i32_16x16x64_i8 v[110:113], v[58:61], v[194:197], v[110:113]
	s_waitcnt lgkmcnt(0)
	v_mfma_i32_16x16x64_i8 v[98:101], v[42:45], v[216:219], v[98:101]
	v_mfma_i32_16x16x64_i8 v[94:97], v[58:61], v[216:219], v[94:97]
	v_mfma_i32_16x16x64_i8 v[138:141], v[142:145], v[166:169], v[138:141]
	v_mfma_i32_16x16x64_i8 v[134:137], v[150:153], v[166:169], v[134:137]
	v_mfma_i32_16x16x64_i8 v[122:125], v[142:145], v[174:177], v[122:125]
	v_mfma_i32_16x16x64_i8 v[118:121], v[150:153], v[174:177], v[118:121]
	v_mfma_i32_16x16x64_i8 v[106:109], v[142:145], v[190:193], v[106:109]
	v_mfma_i32_16x16x64_i8 v[102:105], v[150:153], v[190:193], v[102:105]
	v_mfma_i32_16x16x64_i8 v[90:93], v[142:145], v[198:201], v[90:93]
	v_mfma_i32_16x16x64_i8 v[86:89], v[150:153], v[198:201], v[86:89]
	v_mfma_i32_16x16x64_i8 v[138:141], v[146:149], v[170:173], v[138:141]
	v_mfma_i32_16x16x64_i8 v[134:137], v[154:157], v[170:173], v[134:137]
	v_mfma_i32_16x16x64_i8 v[122:125], v[146:149], v[178:181], v[122:125]
	v_mfma_i32_16x16x64_i8 v[118:121], v[154:157], v[178:181], v[118:121]
	v_mfma_i32_16x16x64_i8 v[106:109], v[146:149], v[194:197], v[106:109]
	v_mfma_i32_16x16x64_i8 v[102:105], v[154:157], v[194:197], v[102:105]
	v_mfma_i32_16x16x64_i8 v[90:93], v[146:149], v[216:219], v[90:93]
	v_mfma_i32_16x16x64_i8 v[86:89], v[154:157], v[216:219], v[86:89]
	s_setprio 0
	s_barrier
	ds_read_b128 v[166:169], v212 offset:16384
	ds_read_b128 v[170:173], v212 offset:17408
	s_mov_b32 m0, s48
	s_nop 0
	buffer_load_dwordx4 v204, s[12:15], s7 offen lds
	ds_read_b128 v[174:177], v212 offset:18432
	ds_read_b128 v[178:181], v212 offset:19456
	s_add_i32 s9, s7, 0x20000
	s_mov_b32 m0, s49
	s_nop 0
	buffer_load_dwordx4 v205, s[12:15], s7 offen lds
	ds_read_b128 v[190:193], v212 offset:20480
	ds_read_b128 v[194:197], v212 offset:21504
	s_nop 0
	s_mov_b32 m0, s50
	s_nop 0
	buffer_load_dwordx4 v204, s[12:15], s9 offen lds
	ds_read_b128 v[198:201], v212 offset:22528
	ds_read_b128 v[216:219], v212 offset:23552
	s_nop 0
	s_mov_b32 m0, s51
	s_nop 0
	buffer_load_dwordx4 v205, s[12:15], s9 offen lds
	s_nop 0
	s_mov_b32 m0, s47
	s_nop 0
	buffer_load_dwordx4 v206, s[16:19], s8 offen lds
	s_nop 0
	s_mov_b32 m0, s52
	s_nop 0
	buffer_load_dwordx4 v207, s[16:19], s8 offen lds
	s_waitcnt vmcnt(8)
	s_waitcnt lgkmcnt(0)
	s_barrier
	s_setprio 1
	s_waitcnt lgkmcnt(7)
	v_mfma_i32_16x16x64_i8 v[82:85], v[38:41], v[166:169], v[82:85]
	v_mfma_i32_16x16x64_i8 v[78:81], v[46:49], v[166:169], v[78:81]
	s_waitcnt lgkmcnt(5)
	v_mfma_i32_16x16x64_i8 v[66:69], v[38:41], v[174:177], v[66:69]
	v_mfma_i32_16x16x64_i8 v[62:65], v[46:49], v[174:177], v[62:65]
	s_waitcnt lgkmcnt(3)
	v_mfma_i32_16x16x64_i8 v[34:37], v[38:41], v[190:193], v[34:37]
	v_mfma_i32_16x16x64_i8 v[30:33], v[46:49], v[190:193], v[30:33]
	s_waitcnt lgkmcnt(1)
	v_mfma_i32_16x16x64_i8 v[18:21], v[38:41], v[198:201], v[18:21]
	v_mfma_i32_16x16x64_i8 v[14:17], v[46:49], v[198:201], v[14:17]
	v_mfma_i32_16x16x64_i8 v[82:85], v[42:45], v[170:173], v[82:85]
	v_mfma_i32_16x16x64_i8 v[78:81], v[58:61], v[170:173], v[78:81]
	v_mfma_i32_16x16x64_i8 v[66:69], v[42:45], v[178:181], v[66:69]
	v_mfma_i32_16x16x64_i8 v[62:65], v[58:61], v[178:181], v[62:65]
	v_mfma_i32_16x16x64_i8 v[34:37], v[42:45], v[194:197], v[34:37]
	v_mfma_i32_16x16x64_i8 v[30:33], v[58:61], v[194:197], v[30:33]
	s_waitcnt lgkmcnt(0)
	v_mfma_i32_16x16x64_i8 v[18:21], v[42:45], v[216:219], v[18:21]
	v_mfma_i32_16x16x64_i8 v[14:17], v[58:61], v[216:219], v[14:17]
	v_mfma_i32_16x16x64_i8 v[50:53], v[150:153], v[174:177], v[50:53]
	v_mfma_i32_16x16x64_i8 v[26:29], v[142:145], v[190:193], v[26:29]
	v_mfma_i32_16x16x64_i8 v[22:25], v[150:153], v[190:193], v[22:25]
	v_mfma_i32_16x16x64_i8 v[10:13], v[142:145], v[198:201], v[10:13]
	v_mfma_i32_16x16x64_i8 v[4:7], v[150:153], v[198:201], v[6:9]
	v_mfma_i32_16x16x64_i8 v[38:41], v[142:145], v[166:169], v[74:77]
	v_mfma_i32_16x16x64_i8 v[42:45], v[150:153], v[166:169], v[70:73]
	v_mfma_i32_16x16x64_i8 v[46:49], v[142:145], v[174:177], v[54:57]
	v_mfma_i32_16x16x64_i8 v[50:53], v[154:157], v[178:181], v[50:53]
	v_mfma_i32_16x16x64_i8 v[26:29], v[146:149], v[194:197], v[26:29]
	v_mfma_i32_16x16x64_i8 v[22:25], v[154:157], v[194:197], v[22:25]
	v_mfma_i32_16x16x64_i8 v[10:13], v[146:149], v[216:219], v[10:13]
	v_mfma_i32_16x16x64_i8 v[4:7], v[154:157], v[216:219], v[4:7]
	v_mfma_i32_16x16x64_i8 v[38:41], v[146:149], v[170:173], v[38:41]
	v_mfma_i32_16x16x64_i8 v[42:45], v[154:157], v[170:173], v[42:45]
	v_mfma_i32_16x16x64_i8 v[46:49], v[146:149], v[178:181], v[46:49]
	s_setprio 0
	s_barrier
	ds_read_b128 v[54:57], v213
	ds_read_b128 v[58:61], v213 offset:1024
	ds_read_b128 v[70:73], v213 offset:2048
	ds_read_b128 v[74:77], v213 offset:3072
	ds_read_b128 v[142:145], v214
	ds_read_b128 v[146:149], v214 offset:1024
	ds_read_b128 v[150:153], v214 offset:2048
	ds_read_b128 v[154:157], v214 offset:3072
	s_add_i32 s8, s8, 0x20000
	s_mov_b32 m0, s53
	s_nop 0
	buffer_load_dwordx4 v206, s[16:19], s8 offen lds
	s_nop 0
	s_mov_b32 m0, s54
	s_nop 0
	buffer_load_dwordx4 v207, s[16:19], s8 offen lds
	ds_read_b128 v[166:169], v212 offset:32768
	ds_read_b128 v[170:173], v212 offset:33792
	ds_read_b128 v[174:177], v212 offset:34816
	ds_read_b128 v[178:181], v212 offset:35840
	ds_read_b128 v[190:193], v212 offset:36864
	ds_read_b128 v[194:197], v212 offset:37888
	ds_read_b128 v[198:201], v212 offset:38912
	ds_read_b128 v[216:219], v212 offset:39936
	s_waitcnt vmcnt(8)
	s_waitcnt lgkmcnt(0)
	s_barrier
	s_setprio 1
	s_waitcnt lgkmcnt(7)
	v_mfma_i32_16x16x64_i8 v[162:165], v[54:57], v[166:169], v[162:165]
	v_mfma_i32_16x16x64_i8 v[158:161], v[70:73], v[166:169], v[158:161]
	s_waitcnt lgkmcnt(5)
	v_mfma_i32_16x16x64_i8 v[130:133], v[54:57], v[174:177], v[130:133]
	v_mfma_i32_16x16x64_i8 v[126:129], v[70:73], v[174:177], v[126:129]
	s_waitcnt lgkmcnt(3)
	v_mfma_i32_16x16x64_i8 v[114:117], v[54:57], v[190:193], v[114:117]
	v_mfma_i32_16x16x64_i8 v[110:113], v[70:73], v[190:193], v[110:113]
	s_waitcnt lgkmcnt(1)
	v_mfma_i32_16x16x64_i8 v[98:101], v[54:57], v[198:201], v[98:101]
	v_mfma_i32_16x16x64_i8 v[94:97], v[70:73], v[198:201], v[94:97]
	v_mfma_i32_16x16x64_i8 v[162:165], v[58:61], v[170:173], v[162:165]
	v_mfma_i32_16x16x64_i8 v[158:161], v[74:77], v[170:173], v[158:161]
	v_mfma_i32_16x16x64_i8 v[130:133], v[58:61], v[178:181], v[130:133]
	v_mfma_i32_16x16x64_i8 v[126:129], v[74:77], v[178:181], v[126:129]
	v_mfma_i32_16x16x64_i8 v[114:117], v[58:61], v[194:197], v[114:117]
	v_mfma_i32_16x16x64_i8 v[110:113], v[74:77], v[194:197], v[110:113]
	s_waitcnt lgkmcnt(0)
	v_mfma_i32_16x16x64_i8 v[98:101], v[58:61], v[216:219], v[98:101]
	v_mfma_i32_16x16x64_i8 v[94:97], v[74:77], v[216:219], v[94:97]
	v_mfma_i32_16x16x64_i8 v[138:141], v[142:145], v[166:169], v[138:141]
	v_mfma_i32_16x16x64_i8 v[134:137], v[150:153], v[166:169], v[134:137]
	v_mfma_i32_16x16x64_i8 v[122:125], v[142:145], v[174:177], v[122:125]
	v_mfma_i32_16x16x64_i8 v[118:121], v[150:153], v[174:177], v[118:121]
	v_mfma_i32_16x16x64_i8 v[106:109], v[142:145], v[190:193], v[106:109]
	v_mfma_i32_16x16x64_i8 v[102:105], v[150:153], v[190:193], v[102:105]
	v_mfma_i32_16x16x64_i8 v[90:93], v[142:145], v[198:201], v[90:93]
	v_mfma_i32_16x16x64_i8 v[86:89], v[150:153], v[198:201], v[86:89]
	v_mfma_i32_16x16x64_i8 v[138:141], v[146:149], v[170:173], v[138:141]
	v_mfma_i32_16x16x64_i8 v[134:137], v[154:157], v[170:173], v[134:137]
	v_mfma_i32_16x16x64_i8 v[122:125], v[146:149], v[178:181], v[122:125]
	v_mfma_i32_16x16x64_i8 v[118:121], v[154:157], v[178:181], v[118:121]
	v_mfma_i32_16x16x64_i8 v[106:109], v[146:149], v[194:197], v[106:109]
	v_mfma_i32_16x16x64_i8 v[102:105], v[154:157], v[194:197], v[102:105]
	v_mfma_i32_16x16x64_i8 v[90:93], v[146:149], v[216:219], v[90:93]
	v_mfma_i32_16x16x64_i8 v[86:89], v[154:157], v[216:219], v[86:89]
	s_setprio 0
	s_barrier
	ds_read_b128 v[166:169], v212 offset:49152
	ds_read_b128 v[170:173], v212 offset:50176
	s_or_b32 s8, s7, 0x80
	s_mov_b32 m0, s62
	s_nop 0
	buffer_load_dwordx4 v204, s[12:15], s8 offen lds
	ds_read_b128 v[174:177], v212 offset:51200
	ds_read_b128 v[178:181], v212 offset:52224
	s_add_i32 s7, s7, 0x20080
	s_mov_b32 m0, s63
	s_nop 0
	buffer_load_dwordx4 v205, s[12:15], s8 offen lds
	ds_read_b128 v[190:193], v212 offset:53248
	ds_read_b128 v[194:197], v212 offset:54272
	s_nop 0
	s_mov_b32 m0, s66
	s_nop 0
	buffer_load_dwordx4 v204, s[12:15], s7 offen lds
	ds_read_b128 v[198:201], v212 offset:55296
	ds_read_b128 v[216:219], v212 offset:56320
	s_nop 0
	s_mov_b32 m0, s67
	s_nop 0
	buffer_load_dwordx4 v205, s[12:15], s7 offen lds
	s_nop 0
	s_mov_b32 m0, s64
	s_nop 0
	buffer_load_dwordx4 v206, s[16:19], s6 offen lds
	s_nop 0
	s_mov_b32 m0, s65
	s_nop 0
	buffer_load_dwordx4 v207, s[16:19], s6 offen lds
	s_waitcnt vmcnt(8)
	s_waitcnt lgkmcnt(0)
	s_barrier
	s_setprio 1
	s_waitcnt lgkmcnt(7)
	v_mfma_i32_16x16x64_i8 v[82:85], v[54:57], v[166:169], v[82:85]
	v_mfma_i32_16x16x64_i8 v[78:81], v[70:73], v[166:169], v[78:81]
	s_waitcnt lgkmcnt(5)
	v_mfma_i32_16x16x64_i8 v[66:69], v[54:57], v[174:177], v[66:69]
	v_mfma_i32_16x16x64_i8 v[62:65], v[70:73], v[174:177], v[62:65]
	s_waitcnt lgkmcnt(3)
	v_mfma_i32_16x16x64_i8 v[34:37], v[54:57], v[190:193], v[34:37]
	v_mfma_i32_16x16x64_i8 v[30:33], v[70:73], v[190:193], v[30:33]
	s_waitcnt lgkmcnt(1)
	v_mfma_i32_16x16x64_i8 v[18:21], v[54:57], v[198:201], v[18:21]
	v_mfma_i32_16x16x64_i8 v[14:17], v[70:73], v[198:201], v[14:17]
	v_mfma_i32_16x16x64_i8 v[82:85], v[58:61], v[170:173], v[82:85]
	v_mfma_i32_16x16x64_i8 v[78:81], v[74:77], v[170:173], v[78:81]
	v_mfma_i32_16x16x64_i8 v[66:69], v[58:61], v[178:181], v[66:69]
	v_mfma_i32_16x16x64_i8 v[62:65], v[74:77], v[178:181], v[62:65]
	v_mfma_i32_16x16x64_i8 v[34:37], v[58:61], v[194:197], v[34:37]
	v_mfma_i32_16x16x64_i8 v[30:33], v[74:77], v[194:197], v[30:33]
	s_waitcnt lgkmcnt(0)
	v_mfma_i32_16x16x64_i8 v[18:21], v[58:61], v[216:219], v[18:21]
	v_mfma_i32_16x16x64_i8 v[14:17], v[74:77], v[216:219], v[14:17]
	v_mfma_i32_16x16x64_i8 v[38:41], v[142:145], v[166:169], v[38:41]
	v_mfma_i32_16x16x64_i8 v[74:77], v[146:149], v[170:173], v[38:41]
	v_mfma_i32_16x16x64_i8 v[38:41], v[150:153], v[166:169], v[42:45]
	v_mfma_i32_16x16x64_i8 v[70:73], v[154:157], v[170:173], v[38:41]
	v_mfma_i32_16x16x64_i8 v[38:41], v[142:145], v[174:177], v[46:49]
	v_mfma_i32_16x16x64_i8 v[54:57], v[146:149], v[178:181], v[38:41]
	v_mfma_i32_16x16x64_i8 v[38:41], v[150:153], v[174:177], v[50:53]
	v_mfma_i32_16x16x64_i8 v[26:29], v[142:145], v[190:193], v[26:29]
	v_mfma_i32_16x16x64_i8 v[22:25], v[150:153], v[190:193], v[22:25]
	v_mfma_i32_16x16x64_i8 v[8:11], v[142:145], v[198:201], v[10:13]
	v_mfma_i32_16x16x64_i8 v[4:7], v[150:153], v[198:201], v[4:7]
	v_mfma_i32_16x16x64_i8 v[50:53], v[154:157], v[178:181], v[38:41]
	v_mfma_i32_16x16x64_i8 v[26:29], v[146:149], v[194:197], v[26:29]
	v_mfma_i32_16x16x64_i8 v[22:25], v[154:157], v[194:197], v[22:25]
	v_mfma_i32_16x16x64_i8 v[10:13], v[146:149], v[216:219], v[8:11]
	v_mfma_i32_16x16x64_i8 v[6:9], v[154:157], v[216:219], v[4:7]
	s_setprio 0
	s_barrier
	s_add_i32 s3, s3, 2
	s_addk_i32 s1, 0x100
	s_addk_i32 s2, 0x100
	s_cmp_gt_u32 s3, 5
	s_cbranch_scc0 .LBB0_619
	s_and_b64 vcc, exec, s[34:35]
	s_cbranch_vccz .LBB0_622
	s_barrier

.LBB0_943:
	v_add_u32_e32 v150, 0x10000, v8
	v_add_u32_e32 v166, 0x14000, v8
	ds_read_b128 v[10:13], v150
	ds_read_b128 v[14:17], v150 offset:1024
	ds_read_b128 v[146:149], v150 offset:2048
	ds_read_b128 v[150:153], v150 offset:3072
	ds_read_b128 v[154:157], v166
	ds_read_b128 v[158:161], v166 offset:1024
	ds_read_b128 v[162:165], v166 offset:2048
	ds_read_b128 v[166:169], v166 offset:3072
	s_add_i32 s61, s37, s58
	s_add_i32 s60, s33, s58
	s_add_i32 s59, s61, 0x400
	s_addk_i32 s60, 0x400
	s_cmp_eq_u32 s58, 0
	s_cselect_b32 s62, s53, s59
	s_cselect_b32 s60, s54, s60
	s_or_b32 s59, s62, 0x80
	s_add_i32 s61, s61, 0x20380
	s_mov_b32 m0, s48
	s_nop 0
	buffer_load_dwordx4 v6, s[12:15], s61 offen lds
	s_nop 0
	s_mov_b32 m0, s49
	s_nop 0
	buffer_load_dwordx4 v7, s[12:15], s61 offen lds
	ds_read_b128 v[170:173], v9
	ds_read_b128 v[174:177], v9 offset:1024
	ds_read_b128 v[178:181], v9 offset:2048
	ds_read_b128 v[182:185], v9 offset:3072
	ds_read_b128 v[186:189], v9 offset:4096
	ds_read_b128 v[190:193], v9 offset:5120
	ds_read_b128 v[194:197], v9 offset:6144
	ds_read_b128 v[198:201], v9 offset:7168
	s_waitcnt vmcnt(8)
	s_waitcnt lgkmcnt(0)
	s_barrier
	s_setprio 1
	s_waitcnt lgkmcnt(7)
	v_mfma_i32_16x16x64_i8 v[142:145], v[10:13], v[170:173], v[142:145]
	v_mfma_i32_16x16x64_i8 v[138:141], v[146:149], v[170:173], v[138:141]
	s_waitcnt lgkmcnt(5)
	v_mfma_i32_16x16x64_i8 v[126:129], v[10:13], v[178:181], v[126:129]
	v_mfma_i32_16x16x64_i8 v[122:125], v[146:149], v[178:181], v[122:125]
	s_waitcnt lgkmcnt(3)
	v_mfma_i32_16x16x64_i8 v[110:113], v[10:13], v[186:189], v[110:113]
	v_mfma_i32_16x16x64_i8 v[106:109], v[146:149], v[186:189], v[106:109]
	s_waitcnt lgkmcnt(1)
	v_mfma_i32_16x16x64_i8 v[94:97], v[10:13], v[194:197], v[94:97]
	v_mfma_i32_16x16x64_i8 v[90:93], v[146:149], v[194:197], v[90:93]
	v_mfma_i32_16x16x64_i8 v[142:145], v[14:17], v[174:177], v[142:145]
	v_mfma_i32_16x16x64_i8 v[138:141], v[150:153], v[174:177], v[138:141]
	v_mfma_i32_16x16x64_i8 v[126:129], v[14:17], v[182:185], v[126:129]
	v_mfma_i32_16x16x64_i8 v[122:125], v[150:153], v[182:185], v[122:125]
	v_mfma_i32_16x16x64_i8 v[110:113], v[14:17], v[190:193], v[110:113]
	v_mfma_i32_16x16x64_i8 v[106:109], v[150:153], v[190:193], v[106:109]
	s_waitcnt lgkmcnt(0)
	v_mfma_i32_16x16x64_i8 v[94:97], v[14:17], v[198:201], v[94:97]
	v_mfma_i32_16x16x64_i8 v[90:93], v[150:153], v[198:201], v[90:93]
	v_mfma_i32_16x16x64_i8 v[134:137], v[154:157], v[170:173], v[134:137]
	v_mfma_i32_16x16x64_i8 v[130:133], v[162:165], v[170:173], v[130:133]
	v_mfma_i32_16x16x64_i8 v[118:121], v[154:157], v[178:181], v[118:121]
	v_mfma_i32_16x16x64_i8 v[114:117], v[162:165], v[178:181], v[114:117]
	v_mfma_i32_16x16x64_i8 v[102:105], v[154:157], v[186:189], v[102:105]
	v_mfma_i32_16x16x64_i8 v[98:101], v[162:165], v[186:189], v[98:101]
	v_mfma_i32_16x16x64_i8 v[86:89], v[154:157], v[194:197], v[86:89]
	v_mfma_i32_16x16x64_i8 v[82:85], v[162:165], v[194:197], v[82:85]
	v_mfma_i32_16x16x64_i8 v[134:137], v[158:161], v[174:177], v[134:137]
	v_mfma_i32_16x16x64_i8 v[130:133], v[166:169], v[174:177], v[130:133]
	v_mfma_i32_16x16x64_i8 v[118:121], v[158:161], v[182:185], v[118:121]
	v_mfma_i32_16x16x64_i8 v[114:117], v[166:169], v[182:185], v[114:117]
	v_mfma_i32_16x16x64_i8 v[102:105], v[158:161], v[190:193], v[102:105]
	v_mfma_i32_16x16x64_i8 v[98:101], v[166:169], v[190:193], v[98:101]
	v_mfma_i32_16x16x64_i8 v[86:89], v[158:161], v[198:201], v[86:89]
	v_mfma_i32_16x16x64_i8 v[82:85], v[166:169], v[198:201], v[82:85]
	s_setprio 0
	s_barrier
	ds_read_b128 v[170:173], v9 offset:16384
	ds_read_b128 v[174:177], v9 offset:17408
	s_mov_b32 m0, s29
	s_nop 0
	buffer_load_dwordx4 v6, s[8:11], s60 offen lds
	ds_read_b128 v[178:181], v9 offset:18432
	ds_read_b128 v[182:185], v9 offset:19456
	s_add_i32 s61, s60, 0x20000
	s_mov_b32 m0, s34
	s_nop 0
	buffer_load_dwordx4 v7, s[8:11], s60 offen lds
	ds_read_b128 v[186:189], v9 offset:20480
	ds_read_b128 v[190:193], v9 offset:21504
	s_nop 0
	s_mov_b32 m0, s35
	s_nop 0
	buffer_load_dwordx4 v6, s[8:11], s61 offen lds
	ds_read_b128 v[194:197], v9 offset:22528
	ds_read_b128 v[198:201], v9 offset:23552
	s_nop 0
	s_mov_b32 m0, s36
	s_nop 0
	buffer_load_dwordx4 v7, s[8:11], s61 offen lds
	s_nop 0
	s_mov_b32 m0, s28
	s_nop 0
	buffer_load_dwordx4 v6, s[12:15], s62 offen lds
	s_nop 0
	s_mov_b32 m0, s38
	s_nop 0
	buffer_load_dwordx4 v7, s[12:15], s62 offen lds
	s_waitcnt vmcnt(8)
	s_waitcnt lgkmcnt(0)
	s_barrier
	s_setprio 1
	s_waitcnt lgkmcnt(7)
	v_mfma_i32_16x16x64_i8 v[78:81], v[10:13], v[170:173], v[78:81]
	v_mfma_i32_16x16x64_i8 v[74:77], v[146:149], v[170:173], v[74:77]
	s_waitcnt lgkmcnt(5)
	v_mfma_i32_16x16x64_i8 v[62:65], v[10:13], v[178:181], v[62:65]
	v_mfma_i32_16x16x64_i8 v[58:61], v[146:149], v[178:181], v[58:61]
	s_waitcnt lgkmcnt(3)
	v_mfma_i32_16x16x64_i8 v[46:49], v[10:13], v[186:189], v[46:49]
	v_mfma_i32_16x16x64_i8 v[42:45], v[146:149], v[186:189], v[42:45]
	s_waitcnt lgkmcnt(1)
	v_mfma_i32_16x16x64_i8 v[10:13], v[10:13], v[194:197], v[30:33]
	v_mfma_i32_16x16x64_i8 v[78:81], v[14:17], v[174:177], v[78:81]
	v_mfma_i32_16x16x64_i8 v[74:77], v[150:153], v[174:177], v[74:77]
	v_mfma_i32_16x16x64_i8 v[62:65], v[14:17], v[182:185], v[62:65]
	v_mfma_i32_16x16x64_i8 v[58:61], v[150:153], v[182:185], v[58:61]
	v_mfma_i32_16x16x64_i8 v[46:49], v[14:17], v[190:193], v[46:49]
	v_mfma_i32_16x16x64_i8 v[42:45], v[150:153], v[190:193], v[42:45]
	s_waitcnt lgkmcnt(0)
	v_mfma_i32_16x16x64_i8 v[10:13], v[14:17], v[198:201], v[10:13]
	v_mfma_i32_16x16x64_i8 v[14:17], v[146:149], v[194:197], v[26:29]
	v_mfma_i32_16x16x64_i8 v[14:17], v[150:153], v[198:201], v[14:17]
	v_mfma_i32_16x16x64_i8 v[26:29], v[154:157], v[170:173], v[70:73]
	v_mfma_i32_16x16x64_i8 v[70:73], v[158:161], v[174:177], v[26:29]
	v_mfma_i32_16x16x64_i8 v[26:29], v[162:165], v[170:173], v[66:69]
	v_mfma_i32_16x16x64_i8 v[66:69], v[166:169], v[174:177], v[26:29]
	v_mfma_i32_16x16x64_i8 v[26:29], v[154:157], v[178:181], v[54:57]
	v_mfma_i32_16x16x64_i8 v[54:57], v[158:161], v[182:185], v[26:29]
	v_mfma_i32_16x16x64_i8 v[26:29], v[162:165], v[178:181], v[50:53]
	v_mfma_i32_16x16x64_i8 v[50:53], v[166:169], v[182:185], v[26:29]
	v_mfma_i32_16x16x64_i8 v[26:29], v[154:157], v[186:189], v[38:41]
	v_mfma_i32_16x16x64_i8 v[38:41], v[158:161], v[190:193], v[26:29]
	v_mfma_i32_16x16x64_i8 v[26:29], v[162:165], v[186:189], v[34:37]
	v_mfma_i32_16x16x64_i8 v[22:25], v[154:157], v[194:197], v[22:25]
	v_mfma_i32_16x16x64_i8 v[18:21], v[162:165], v[194:197], v[18:21]
	v_mfma_i32_16x16x64_i8 v[34:37], v[166:169], v[190:193], v[26:29]
	v_mfma_i32_16x16x64_i8 v[22:25], v[158:161], v[198:201], v[22:25]
	v_mfma_i32_16x16x64_i8 v[18:21], v[166:169], v[198:201], v[18:21]
	s_setprio 0
	s_barrier
	v_add_u32_e32 v150, 0x18000, v8
	v_add_u32_e32 v166, 0x1c000, v8
	ds_read_b128 v[26:29], v150
	ds_read_b128 v[30:33], v150 offset:1024
	ds_read_b128 v[146:149], v150 offset:2048
	ds_read_b128 v[150:153], v150 offset:3072
	ds_read_b128 v[154:157], v166
	ds_read_b128 v[158:161], v166 offset:1024
	ds_read_b128 v[162:165], v166 offset:2048
	ds_read_b128 v[166:169], v166 offset:3072
	s_add_i32 s61, s62, 0x20000
	s_mov_b32 m0, s40
	s_nop 0
	buffer_load_dwordx4 v6, s[12:15], s61 offen lds
	s_nop 0
	s_mov_b32 m0, s41
	s_nop 0
	buffer_load_dwordx4 v7, s[12:15], s61 offen lds
	ds_read_b128 v[170:173], v9 offset:32768
	ds_read_b128 v[174:177], v9 offset:33792
	ds_read_b128 v[178:181], v9 offset:34816
	ds_read_b128 v[182:185], v9 offset:35840
	ds_read_b128 v[186:189], v9 offset:36864
	ds_read_b128 v[190:193], v9 offset:37888
	ds_read_b128 v[194:197], v9 offset:38912
	ds_read_b128 v[198:201], v9 offset:39936
	s_waitcnt vmcnt(8)
	s_waitcnt lgkmcnt(0)
	s_barrier
	s_setprio 1
	s_waitcnt lgkmcnt(7)
	v_mfma_i32_16x16x64_i8 v[142:145], v[26:29], v[170:173], v[142:145]
	v_mfma_i32_16x16x64_i8 v[138:141], v[146:149], v[170:173], v[138:141]
	s_waitcnt lgkmcnt(5)
	v_mfma_i32_16x16x64_i8 v[126:129], v[26:29], v[178:181], v[126:129]
	v_mfma_i32_16x16x64_i8 v[122:125], v[146:149], v[178:181], v[122:125]
	s_waitcnt lgkmcnt(3)
	v_mfma_i32_16x16x64_i8 v[110:113], v[26:29], v[186:189], v[110:113]
	v_mfma_i32_16x16x64_i8 v[106:109], v[146:149], v[186:189], v[106:109]
	s_waitcnt lgkmcnt(1)
	v_mfma_i32_16x16x64_i8 v[94:97], v[26:29], v[194:197], v[94:97]
	v_mfma_i32_16x16x64_i8 v[90:93], v[146:149], v[194:197], v[90:93]
	v_mfma_i32_16x16x64_i8 v[142:145], v[30:33], v[174:177], v[142:145]
	v_mfma_i32_16x16x64_i8 v[138:141], v[150:153], v[174:177], v[138:141]
	v_mfma_i32_16x16x64_i8 v[126:129], v[30:33], v[182:185], v[126:129]
	v_mfma_i32_16x16x64_i8 v[122:125], v[150:153], v[182:185], v[122:125]
	v_mfma_i32_16x16x64_i8 v[110:113], v[30:33], v[190:193], v[110:113]
	v_mfma_i32_16x16x64_i8 v[106:109], v[150:153], v[190:193], v[106:109]
	s_waitcnt lgkmcnt(0)
	v_mfma_i32_16x16x64_i8 v[94:97], v[30:33], v[198:201], v[94:97]
	v_mfma_i32_16x16x64_i8 v[90:93], v[150:153], v[198:201], v[90:93]
	v_mfma_i32_16x16x64_i8 v[134:137], v[154:157], v[170:173], v[134:137]
	v_mfma_i32_16x16x64_i8 v[130:133], v[162:165], v[170:173], v[130:133]
	v_mfma_i32_16x16x64_i8 v[118:121], v[154:157], v[178:181], v[118:121]
	v_mfma_i32_16x16x64_i8 v[114:117], v[162:165], v[178:181], v[114:117]
	v_mfma_i32_16x16x64_i8 v[102:105], v[154:157], v[186:189], v[102:105]
	v_mfma_i32_16x16x64_i8 v[98:101], v[162:165], v[186:189], v[98:101]
	v_mfma_i32_16x16x64_i8 v[86:89], v[154:157], v[194:197], v[86:89]
	v_mfma_i32_16x16x64_i8 v[82:85], v[162:165], v[194:197], v[82:85]
	v_mfma_i32_16x16x64_i8 v[134:137], v[158:161], v[174:177], v[134:137]
	v_mfma_i32_16x16x64_i8 v[130:133], v[166:169], v[174:177], v[130:133]
	v_mfma_i32_16x16x64_i8 v[118:121], v[158:161], v[182:185], v[118:121]
	v_mfma_i32_16x16x64_i8 v[114:117], v[166:169], v[182:185], v[114:117]
	v_mfma_i32_16x16x64_i8 v[102:105], v[158:161], v[190:193], v[102:105]
	v_mfma_i32_16x16x64_i8 v[98:101], v[166:169], v[190:193], v[98:101]
	v_mfma_i32_16x16x64_i8 v[86:89], v[158:161], v[198:201], v[86:89]
	v_mfma_i32_16x16x64_i8 v[82:85], v[166:169], v[198:201], v[82:85]
	s_setprio 0
	s_barrier
	ds_read_b128 v[170:173], v9 offset:49152
	ds_read_b128 v[174:177], v9 offset:50176
	s_or_b32 s61, s60, 0x80
	s_mov_b32 m0, s42
	s_nop 0
	buffer_load_dwordx4 v6, s[8:11], s61 offen lds
	ds_read_b128 v[178:181], v9 offset:51200
	ds_read_b128 v[182:185], v9 offset:52224
	s_add_i32 s60, s60, 0x20080
	s_mov_b32 m0, s43
	s_nop 0
	buffer_load_dwordx4 v7, s[8:11], s61 offen lds
	ds_read_b128 v[186:189], v9 offset:53248
	ds_read_b128 v[190:193], v9 offset:54272
	s_nop 0
	s_mov_b32 m0, s46
	s_nop 0
	buffer_load_dwordx4 v6, s[8:11], s60 offen lds
	ds_read_b128 v[194:197], v9 offset:55296
	ds_read_b128 v[198:201], v9 offset:56320
	s_nop 0
	s_mov_b32 m0, s47
	s_nop 0
	buffer_load_dwordx4 v7, s[8:11], s60 offen lds
	s_nop 0
	s_mov_b32 m0, s44
	s_nop 0
	buffer_load_dwordx4 v6, s[12:15], s59 offen lds
	s_nop 0
	s_mov_b32 m0, s45
	s_nop 0
	buffer_load_dwordx4 v7, s[12:15], s59 offen lds
	s_waitcnt vmcnt(8)
	s_waitcnt lgkmcnt(0)
	s_barrier
	s_setprio 1
	s_waitcnt lgkmcnt(7)
	v_mfma_i32_16x16x64_i8 v[78:81], v[26:29], v[170:173], v[78:81]
	s_waitcnt lgkmcnt(5)
	v_mfma_i32_16x16x64_i8 v[62:65], v[26:29], v[178:181], v[62:65]
	s_waitcnt lgkmcnt(3)
	v_mfma_i32_16x16x64_i8 v[46:49], v[26:29], v[186:189], v[46:49]
	s_waitcnt lgkmcnt(1)
	v_mfma_i32_16x16x64_i8 v[10:13], v[26:29], v[194:197], v[10:13]
	v_mfma_i32_16x16x64_i8 v[78:81], v[30:33], v[174:177], v[78:81]
	v_mfma_i32_16x16x64_i8 v[74:77], v[146:149], v[170:173], v[74:77]
	v_mfma_i32_16x16x64_i8 v[62:65], v[30:33], v[182:185], v[62:65]
	v_mfma_i32_16x16x64_i8 v[58:61], v[146:149], v[178:181], v[58:61]
	v_mfma_i32_16x16x64_i8 v[46:49], v[30:33], v[190:193], v[46:49]
	v_mfma_i32_16x16x64_i8 v[42:45], v[146:149], v[186:189], v[42:45]
	s_waitcnt lgkmcnt(0)
	v_mfma_i32_16x16x64_i8 v[30:33], v[30:33], v[198:201], v[10:13]
	v_mfma_i32_16x16x64_i8 v[10:13], v[146:149], v[194:197], v[14:17]
	v_mfma_i32_16x16x64_i8 v[74:77], v[150:153], v[174:177], v[74:77]
	v_mfma_i32_16x16x64_i8 v[58:61], v[150:153], v[182:185], v[58:61]
	v_mfma_i32_16x16x64_i8 v[42:45], v[150:153], v[190:193], v[42:45]
	v_mfma_i32_16x16x64_i8 v[26:29], v[150:153], v[198:201], v[10:13]
	v_mfma_i32_16x16x64_i8 v[10:13], v[154:157], v[170:173], v[70:73]
	v_mfma_i32_16x16x64_i8 v[70:73], v[158:161], v[174:177], v[10:13]
	v_mfma_i32_16x16x64_i8 v[10:13], v[162:165], v[170:173], v[66:69]
	v_mfma_i32_16x16x64_i8 v[66:69], v[166:169], v[174:177], v[10:13]
	v_mfma_i32_16x16x64_i8 v[10:13], v[154:157], v[178:181], v[54:57]
	v_mfma_i32_16x16x64_i8 v[54:57], v[158:161], v[182:185], v[10:13]
	v_mfma_i32_16x16x64_i8 v[10:13], v[162:165], v[178:181], v[50:53]
	v_mfma_i32_16x16x64_i8 v[50:53], v[166:169], v[182:185], v[10:13]
	v_mfma_i32_16x16x64_i8 v[10:13], v[154:157], v[186:189], v[38:41]
	v_mfma_i32_16x16x64_i8 v[38:41], v[158:161], v[190:193], v[10:13]
	v_mfma_i32_16x16x64_i8 v[10:13], v[162:165], v[186:189], v[34:37]
	v_mfma_i32_16x16x64_i8 v[34:37], v[166:169], v[190:193], v[10:13]
	v_mfma_i32_16x16x64_i8 v[10:13], v[154:157], v[194:197], v[22:25]
	v_mfma_i32_16x16x64_i8 v[22:25], v[158:161], v[198:201], v[10:13]
	v_mfma_i32_16x16x64_i8 v[10:13], v[162:165], v[194:197], v[18:21]
	v_mfma_i32_16x16x64_i8 v[18:21], v[166:169], v[198:201], v[10:13]
	s_setprio 0
	s_barrier
	s_add_i32 s55, s55, 2
	s_addk_i32 s58, 0x100
	s_cmp_lt_u32 s55, 6
	s_cbranch_scc1 .LBB0_943
	s_andn2_b64 vcc, exec, s[6:7]
	s_cbranch_vccz .LBB0_935
	v_cvt_f32_i32_e32 v142, v142
	v_cvt_f32_i32_e32 v143, v143
	v_cvt_f32_i32_e32 v144, v144
	v_cvt_f32_i32_e32 v145, v145
	v_cvt_f32_i32_e32 v138, v138
	v_cvt_f32_i32_e32 v139, v139
	v_cvt_f32_i32_e32 v140, v140
	v_cvt_f32_i32_e32 v141, v141
	v_cvt_f32_i32_e32 v126, v126
	v_cvt_f32_i32_e32 v127, v127
	v_cvt_f32_i32_e32 v128, v128
	v_cvt_f32_i32_e32 v129, v129
	v_cvt_f32_i32_e32 v122, v122
	v_cvt_f32_i32_e32 v123, v123
	v_cvt_f32_i32_e32 v124, v124
	v_cvt_f32_i32_e32 v125, v125
	v_cvt_f32_i32_e32 v110, v110
	v_cvt_f32_i32_e32 v111, v111
	v_cvt_f32_i32_e32 v112, v112
	v_cvt_f32_i32_e32 v113, v113
	v_cvt_f32_i32_e32 v106, v106
	v_cvt_f32_i32_e32 v107, v107
	v_cvt_f32_i32_e32 v108, v108
	v_cvt_f32_i32_e32 v109, v109
	v_cvt_f32_i32_e32 v94, v94
	v_cvt_f32_i32_e32 v95, v95
	v_cvt_f32_i32_e32 v96, v96
	v_cvt_f32_i32_e32 v97, v97
	v_cvt_f32_i32_e32 v90, v90
	v_cvt_f32_i32_e32 v91, v91
	v_cvt_f32_i32_e32 v92, v92
	v_cvt_f32_i32_e32 v93, v93
	v_cvt_f32_i32_e32 v134, v134
	v_cvt_f32_i32_e32 v135, v135
	v_cvt_f32_i32_e32 v136, v136
	v_cvt_f32_i32_e32 v137, v137
	v_cvt_f32_i32_e32 v130, v130
	v_cvt_f32_i32_e32 v131, v131
	v_cvt_f32_i32_e32 v132, v132
	v_cvt_f32_i32_e32 v133, v133
	v_cvt_f32_i32_e32 v118, v118
	v_cvt_f32_i32_e32 v119, v119
	v_cvt_f32_i32_e32 v120, v120
	v_cvt_f32_i32_e32 v121, v121
	v_cvt_f32_i32_e32 v114, v114
	v_cvt_f32_i32_e32 v115, v115
	v_cvt_f32_i32_e32 v116, v116
	v_cvt_f32_i32_e32 v117, v117
	v_cvt_f32_i32_e32 v102, v102
	v_cvt_f32_i32_e32 v103, v103
	v_cvt_f32_i32_e32 v104, v104
	v_cvt_f32_i32_e32 v105, v105
	v_cvt_f32_i32_e32 v98, v98
	v_cvt_f32_i32_e32 v99, v99
	v_cvt_f32_i32_e32 v100, v100
	v_cvt_f32_i32_e32 v101, v101
	v_cvt_f32_i32_e32 v86, v86
	v_cvt_f32_i32_e32 v87, v87
	v_cvt_f32_i32_e32 v88, v88
	v_cvt_f32_i32_e32 v89, v89
	v_cvt_f32_i32_e32 v82, v82
	v_cvt_f32_i32_e32 v83, v83
	v_cvt_f32_i32_e32 v84, v84
	v_cvt_f32_i32_e32 v85, v85
	v_cvt_f32_i32_e32 v78, v78
	v_cvt_f32_i32_e32 v79, v79
	v_cvt_f32_i32_e32 v80, v80
	v_cvt_f32_i32_e32 v81, v81
	v_cvt_f32_i32_e32 v74, v74
	v_cvt_f32_i32_e32 v75, v75
	v_cvt_f32_i32_e32 v76, v76
	v_cvt_f32_i32_e32 v77, v77
	v_cvt_f32_i32_e32 v62, v62
	v_cvt_f32_i32_e32 v63, v63
	v_cvt_f32_i32_e32 v64, v64
	v_cvt_f32_i32_e32 v65, v65
	v_cvt_f32_i32_e32 v58, v58
	v_cvt_f32_i32_e32 v59, v59
	v_cvt_f32_i32_e32 v60, v60
	v_cvt_f32_i32_e32 v61, v61
	v_cvt_f32_i32_e32 v46, v46
	v_cvt_f32_i32_e32 v47, v47
	v_cvt_f32_i32_e32 v48, v48
	v_cvt_f32_i32_e32 v49, v49
	v_cvt_f32_i32_e32 v42, v42
	v_cvt_f32_i32_e32 v43, v43
	v_cvt_f32_i32_e32 v44, v44
	v_cvt_f32_i32_e32 v45, v45
	v_cvt_f32_i32_e32 v30, v30
	v_cvt_f32_i32_e32 v31, v31
	v_cvt_f32_i32_e32 v32, v32
	v_cvt_f32_i32_e32 v33, v33
	v_cvt_f32_i32_e32 v26, v26
	v_cvt_f32_i32_e32 v27, v27
	v_cvt_f32_i32_e32 v28, v28
	v_cvt_f32_i32_e32 v29, v29
	v_cvt_f32_i32_e32 v70, v70
	v_cvt_f32_i32_e32 v71, v71
	v_cvt_f32_i32_e32 v72, v72
	v_cvt_f32_i32_e32 v73, v73
	v_cvt_f32_i32_e32 v66, v66
	v_cvt_f32_i32_e32 v67, v67
	v_cvt_f32_i32_e32 v68, v68
	v_cvt_f32_i32_e32 v69, v69
	v_cvt_f32_i32_e32 v54, v54
	v_cvt_f32_i32_e32 v55, v55
	v_cvt_f32_i32_e32 v56, v56
	v_cvt_f32_i32_e32 v57, v57
	v_cvt_f32_i32_e32 v50, v50
	v_cvt_f32_i32_e32 v51, v51
	v_cvt_f32_i32_e32 v52, v52
	v_cvt_f32_i32_e32 v53, v53
	v_cvt_f32_i32_e32 v38, v38
	v_cvt_f32_i32_e32 v39, v39
	v_cvt_f32_i32_e32 v40, v40
	v_cvt_f32_i32_e32 v41, v41
	v_cvt_f32_i32_e32 v34, v34
	v_cvt_f32_i32_e32 v35, v35
	v_cvt_f32_i32_e32 v36, v36
	v_cvt_f32_i32_e32 v37, v37
	v_cvt_f32_i32_e32 v22, v22
	v_cvt_f32_i32_e32 v23, v23
	v_cvt_f32_i32_e32 v24, v24
	v_cvt_f32_i32_e32 v25, v25
	v_cvt_f32_i32_e32 v18, v18
	v_cvt_f32_i32_e32 v19, v19
	v_cvt_f32_i32_e32 v20, v20
	v_cvt_f32_i32_e32 v21, v21
	s_andn2_b64 vcc, exec, s[4:5]
	s_cbranch_vccnz .LBB0_936

.LBB0_1072:
	ds_read_b128 v[136:139], v152
	ds_read_b128 v[140:143], v152 offset:1024
	ds_read_b128 v[158:161], v152 offset:2048
	ds_read_b128 v[162:165], v152 offset:3072
	ds_read_b128 v[166:169], v153
	ds_read_b128 v[170:173], v153 offset:1024
	ds_read_b128 v[174:177], v153 offset:2048
	ds_read_b128 v[178:181], v153 offset:3072
	s_add_i32 s60, s55, 0xfffe0080
	s_cmp_eq_u32 s59, 4
	s_cselect_b32 s62, s1, s60
	s_cselect_b32 s61, s54, s58
	s_or_b32 s60, s62, 0x80
	s_mov_b32 m0, s42
	s_nop 0
	buffer_load_dwordx4 v146, s[12:15], s55 offen lds
	s_nop 0
	s_mov_b32 m0, s43
	s_nop 0
	buffer_load_dwordx4 v147, s[12:15], s55 offen lds
	ds_read_b128 v[182:185], v154
	ds_read_b128 v[186:189], v154 offset:1024
	ds_read_b128 v[190:193], v154 offset:2048
	ds_read_b128 v[194:197], v154 offset:3072
	ds_read_b128 v[198:201], v154 offset:4096
	ds_read_b128 v[202:205], v154 offset:5120
	ds_read_b128 v[206:209], v154 offset:6144
	ds_read_b128 v[210:213], v154 offset:7168
	s_waitcnt vmcnt(8)
	s_waitcnt lgkmcnt(0)
	s_barrier
	s_setprio 1
	s_waitcnt lgkmcnt(0)
	v_mfma_i32_16x16x64_i8 v[126:129], v[136:139], v[182:185], v[126:129]
	v_mfma_i32_16x16x64_i8 v[122:125], v[158:161], v[182:185], v[122:125]
	v_mfma_i32_16x16x64_i8 v[118:121], v[136:139], v[190:193], v[118:121]
	v_mfma_i32_16x16x64_i8 v[114:117], v[158:161], v[190:193], v[114:117]
	v_mfma_i32_16x16x64_i8 v[110:113], v[136:139], v[198:201], v[110:113]
	v_mfma_i32_16x16x64_i8 v[106:109], v[158:161], v[198:201], v[106:109]
	v_mfma_i32_16x16x64_i8 v[102:105], v[136:139], v[206:209], v[102:105]
	v_mfma_i32_16x16x64_i8 v[98:101], v[158:161], v[206:209], v[98:101]
	v_mfma_i32_16x16x64_i8 v[126:129], v[140:143], v[186:189], v[126:129]
	v_mfma_i32_16x16x64_i8 v[122:125], v[162:165], v[186:189], v[122:125]
	v_mfma_i32_16x16x64_i8 v[118:121], v[140:143], v[194:197], v[118:121]
	v_mfma_i32_16x16x64_i8 v[114:117], v[162:165], v[194:197], v[114:117]
	v_mfma_i32_16x16x64_i8 v[110:113], v[140:143], v[202:205], v[110:113]
	v_mfma_i32_16x16x64_i8 v[106:109], v[162:165], v[202:205], v[106:109]
	v_mfma_i32_16x16x64_i8 v[102:105], v[140:143], v[210:213], v[102:105]
	v_mfma_i32_16x16x64_i8 v[98:101], v[162:165], v[210:213], v[98:101]
	v_mfma_i32_16x16x64_i8 v[94:97], v[166:169], v[182:185], v[94:97]
	v_mfma_i32_16x16x64_i8 v[90:93], v[174:177], v[182:185], v[90:93]
	v_mfma_i32_16x16x64_i8 v[86:89], v[166:169], v[190:193], v[86:89]
	v_mfma_i32_16x16x64_i8 v[82:85], v[174:177], v[190:193], v[82:85]
	v_mfma_i32_16x16x64_i8 v[78:81], v[166:169], v[198:201], v[78:81]
	v_mfma_i32_16x16x64_i8 v[74:77], v[174:177], v[198:201], v[74:77]
	v_mfma_i32_16x16x64_i8 v[70:73], v[166:169], v[206:209], v[70:73]
	v_mfma_i32_16x16x64_i8 v[66:69], v[174:177], v[206:209], v[66:69]
	v_mfma_i32_16x16x64_i8 v[94:97], v[170:173], v[186:189], v[94:97]
	v_mfma_i32_16x16x64_i8 v[90:93], v[178:181], v[186:189], v[90:93]
	v_mfma_i32_16x16x64_i8 v[86:89], v[170:173], v[194:197], v[86:89]
	v_mfma_i32_16x16x64_i8 v[82:85], v[178:181], v[194:197], v[82:85]
	v_mfma_i32_16x16x64_i8 v[78:81], v[170:173], v[202:205], v[78:81]
	v_mfma_i32_16x16x64_i8 v[74:77], v[178:181], v[202:205], v[74:77]
	v_mfma_i32_16x16x64_i8 v[70:73], v[170:173], v[210:213], v[70:73]
	v_mfma_i32_16x16x64_i8 v[66:69], v[178:181], v[210:213], v[66:69]
	s_setprio 0
	s_barrier
	ds_read_b128 v[182:185], v154 offset:16384
	ds_read_b128 v[186:189], v154 offset:17408
	s_mov_b32 m0, s27
	s_nop 0
	buffer_load_dwordx4 v144, s[8:11], s61 offen lds
	ds_read_b128 v[190:193], v154 offset:18432
	ds_read_b128 v[194:197], v154 offset:19456
	s_add_i32 s63, s61, 0x20000
	s_mov_b32 m0, s28
	s_nop 0
	buffer_load_dwordx4 v145, s[8:11], s61 offen lds
	ds_read_b128 v[198:201], v154 offset:20480
	ds_read_b128 v[202:205], v154 offset:21504
	s_nop 0
	s_mov_b32 m0, s29
	s_nop 0
	buffer_load_dwordx4 v144, s[8:11], s63 offen lds
	ds_read_b128 v[206:209], v154 offset:22528
	ds_read_b128 v[210:213], v154 offset:23552
	s_nop 0
	s_mov_b32 m0, s30
	s_nop 0
	buffer_load_dwordx4 v145, s[8:11], s63 offen lds
	s_nop 0
	s_mov_b32 m0, s26
	s_nop 0
	buffer_load_dwordx4 v146, s[12:15], s62 offen lds
	s_nop 0
	s_mov_b32 m0, s2
	s_nop 0
	buffer_load_dwordx4 v147, s[12:15], s62 offen lds
	s_waitcnt vmcnt(8)
	s_waitcnt lgkmcnt(0)
	s_barrier
	s_setprio 1
	s_waitcnt lgkmcnt(0)
	v_mfma_i32_16x16x64_i8 v[62:65], v[136:139], v[182:185], v[62:65]
	v_mfma_i32_16x16x64_i8 v[58:61], v[158:161], v[182:185], v[58:61]
	v_mfma_i32_16x16x64_i8 v[54:57], v[136:139], v[190:193], v[54:57]
	v_mfma_i32_16x16x64_i8 v[50:53], v[158:161], v[190:193], v[50:53]
	v_mfma_i32_16x16x64_i8 v[46:49], v[136:139], v[198:201], v[46:49]
	v_mfma_i32_16x16x64_i8 v[42:45], v[158:161], v[198:201], v[42:45]
	v_mfma_i32_16x16x64_i8 v[38:41], v[136:139], v[206:209], v[38:41]
	v_mfma_i32_16x16x64_i8 v[34:37], v[158:161], v[206:209], v[34:37]
	v_mfma_i32_16x16x64_i8 v[62:65], v[140:143], v[186:189], v[62:65]
	v_mfma_i32_16x16x64_i8 v[58:61], v[162:165], v[186:189], v[58:61]
	v_mfma_i32_16x16x64_i8 v[54:57], v[140:143], v[194:197], v[54:57]
	v_mfma_i32_16x16x64_i8 v[50:53], v[162:165], v[194:197], v[50:53]
	v_mfma_i32_16x16x64_i8 v[46:49], v[140:143], v[202:205], v[46:49]
	v_mfma_i32_16x16x64_i8 v[42:45], v[162:165], v[202:205], v[42:45]
	v_mfma_i32_16x16x64_i8 v[38:41], v[140:143], v[210:213], v[38:41]
	v_mfma_i32_16x16x64_i8 v[34:37], v[162:165], v[210:213], v[34:37]
	v_mfma_i32_16x16x64_i8 v[30:33], v[166:169], v[182:185], v[30:33]
	v_mfma_i32_16x16x64_i8 v[26:29], v[174:177], v[182:185], v[26:29]
	v_mfma_i32_16x16x64_i8 v[22:25], v[166:169], v[190:193], v[22:25]
	v_mfma_i32_16x16x64_i8 v[18:21], v[174:177], v[190:193], v[18:21]
	v_mfma_i32_16x16x64_i8 v[14:17], v[166:169], v[198:201], v[14:17]
	v_mfma_i32_16x16x64_i8 v[10:13], v[174:177], v[198:201], v[10:13]
	v_mfma_i32_16x16x64_i8 v[6:9], v[166:169], v[206:209], v[6:9]
	v_mfma_i32_16x16x64_i8 v[2:5], v[174:177], v[206:209], v[2:5]
	v_mfma_i32_16x16x64_i8 v[30:33], v[170:173], v[186:189], v[30:33]
	v_mfma_i32_16x16x64_i8 v[26:29], v[178:181], v[186:189], v[26:29]
	v_mfma_i32_16x16x64_i8 v[22:25], v[170:173], v[194:197], v[22:25]
	v_mfma_i32_16x16x64_i8 v[18:21], v[178:181], v[194:197], v[18:21]
	v_mfma_i32_16x16x64_i8 v[14:17], v[170:173], v[202:205], v[14:17]
	v_mfma_i32_16x16x64_i8 v[10:13], v[178:181], v[202:205], v[10:13]
	v_mfma_i32_16x16x64_i8 v[6:9], v[170:173], v[210:213], v[6:9]
	v_mfma_i32_16x16x64_i8 v[2:5], v[178:181], v[210:213], v[2:5]
	s_setprio 0
	s_barrier
	ds_read_b128 v[136:139], v155
	ds_read_b128 v[140:143], v155 offset:1024
	ds_read_b128 v[158:161], v155 offset:2048
	ds_read_b128 v[162:165], v155 offset:3072
	ds_read_b128 v[166:169], v156
	ds_read_b128 v[170:173], v156 offset:1024
	ds_read_b128 v[174:177], v156 offset:2048
	ds_read_b128 v[178:181], v156 offset:3072
	s_add_i32 s62, s62, 0x20000
	s_mov_b32 m0, s3
	s_nop 0
	buffer_load_dwordx4 v146, s[12:15], s62 offen lds
	s_nop 0
	s_mov_b32 m0, s31
	s_nop 0
	buffer_load_dwordx4 v147, s[12:15], s62 offen lds
	ds_read_b128 v[182:185], v154 offset:32768
	ds_read_b128 v[186:189], v154 offset:33792
	ds_read_b128 v[190:193], v154 offset:34816
	ds_read_b128 v[194:197], v154 offset:35840
	ds_read_b128 v[198:201], v154 offset:36864
	ds_read_b128 v[202:205], v154 offset:37888
	ds_read_b128 v[206:209], v154 offset:38912
	ds_read_b128 v[210:213], v154 offset:39936
	s_waitcnt vmcnt(8)
	s_waitcnt lgkmcnt(0)
	s_barrier
	s_setprio 1
	s_waitcnt lgkmcnt(0)
	v_mfma_i32_16x16x64_i8 v[126:129], v[136:139], v[182:185], v[126:129]
	v_mfma_i32_16x16x64_i8 v[122:125], v[158:161], v[182:185], v[122:125]
	v_mfma_i32_16x16x64_i8 v[118:121], v[136:139], v[190:193], v[118:121]
	v_mfma_i32_16x16x64_i8 v[114:117], v[158:161], v[190:193], v[114:117]
	v_mfma_i32_16x16x64_i8 v[110:113], v[136:139], v[198:201], v[110:113]
	v_mfma_i32_16x16x64_i8 v[106:109], v[158:161], v[198:201], v[106:109]
	v_mfma_i32_16x16x64_i8 v[102:105], v[136:139], v[206:209], v[102:105]
	v_mfma_i32_16x16x64_i8 v[98:101], v[158:161], v[206:209], v[98:101]
	v_mfma_i32_16x16x64_i8 v[126:129], v[140:143], v[186:189], v[126:129]
	v_mfma_i32_16x16x64_i8 v[122:125], v[162:165], v[186:189], v[122:125]
	v_mfma_i32_16x16x64_i8 v[118:121], v[140:143], v[194:197], v[118:121]
	v_mfma_i32_16x16x64_i8 v[114:117], v[162:165], v[194:197], v[114:117]
	v_mfma_i32_16x16x64_i8 v[110:113], v[140:143], v[202:205], v[110:113]
	v_mfma_i32_16x16x64_i8 v[106:109], v[162:165], v[202:205], v[106:109]
	v_mfma_i32_16x16x64_i8 v[102:105], v[140:143], v[210:213], v[102:105]
	v_mfma_i32_16x16x64_i8 v[98:101], v[162:165], v[210:213], v[98:101]
	v_mfma_i32_16x16x64_i8 v[94:97], v[166:169], v[182:185], v[94:97]
	v_mfma_i32_16x16x64_i8 v[90:93], v[174:177], v[182:185], v[90:93]
	v_mfma_i32_16x16x64_i8 v[86:89], v[166:169], v[190:193], v[86:89]
	v_mfma_i32_16x16x64_i8 v[82:85], v[174:177], v[190:193], v[82:85]
	v_mfma_i32_16x16x64_i8 v[78:81], v[166:169], v[198:201], v[78:81]
	v_mfma_i32_16x16x64_i8 v[74:77], v[174:177], v[198:201], v[74:77]
	v_mfma_i32_16x16x64_i8 v[70:73], v[166:169], v[206:209], v[70:73]
	v_mfma_i32_16x16x64_i8 v[66:69], v[174:177], v[206:209], v[66:69]
	v_mfma_i32_16x16x64_i8 v[94:97], v[170:173], v[186:189], v[94:97]
	v_mfma_i32_16x16x64_i8 v[90:93], v[178:181], v[186:189], v[90:93]
	v_mfma_i32_16x16x64_i8 v[86:89], v[170:173], v[194:197], v[86:89]
	v_mfma_i32_16x16x64_i8 v[82:85], v[178:181], v[194:197], v[82:85]
	v_mfma_i32_16x16x64_i8 v[78:81], v[170:173], v[202:205], v[78:81]
	v_mfma_i32_16x16x64_i8 v[74:77], v[178:181], v[202:205], v[74:77]
	v_mfma_i32_16x16x64_i8 v[70:73], v[170:173], v[210:213], v[70:73]
	v_mfma_i32_16x16x64_i8 v[66:69], v[178:181], v[210:213], v[66:69]
	s_setprio 0
	s_barrier
	ds_read_b128 v[182:185], v154 offset:49152
	ds_read_b128 v[186:189], v154 offset:50176
	s_or_b32 s62, s61, 0x80
	s_mov_b32 m0, s35
	s_nop 0
	buffer_load_dwordx4 v144, s[8:11], s62 offen lds
	ds_read_b128 v[190:193], v154 offset:51200
	ds_read_b128 v[194:197], v154 offset:52224
	s_add_i32 s61, s61, 0x20080
	s_mov_b32 m0, s36
	s_nop 0
	buffer_load_dwordx4 v145, s[8:11], s62 offen lds
	ds_read_b128 v[198:201], v154 offset:53248
	ds_read_b128 v[202:205], v154 offset:54272
	s_nop 0
	s_mov_b32 m0, s39
	s_nop 0
	buffer_load_dwordx4 v144, s[8:11], s61 offen lds
	ds_read_b128 v[206:209], v154 offset:55296
	ds_read_b128 v[210:213], v154 offset:56320
	s_nop 0
	s_mov_b32 m0, s40
	s_nop 0
	buffer_load_dwordx4 v145, s[8:11], s61 offen lds
	s_nop 0
	s_mov_b32 m0, s37
	s_nop 0
	buffer_load_dwordx4 v146, s[12:15], s60 offen lds
	s_nop 0
	s_mov_b32 m0, s38
	s_nop 0
	buffer_load_dwordx4 v147, s[12:15], s60 offen lds
	s_waitcnt vmcnt(8)
	s_waitcnt lgkmcnt(0)
	s_barrier
	s_setprio 1
	s_waitcnt lgkmcnt(0)
	v_mfma_i32_16x16x64_i8 v[62:65], v[136:139], v[182:185], v[62:65]
	v_mfma_i32_16x16x64_i8 v[58:61], v[158:161], v[182:185], v[58:61]
	v_mfma_i32_16x16x64_i8 v[54:57], v[136:139], v[190:193], v[54:57]
	v_mfma_i32_16x16x64_i8 v[50:53], v[158:161], v[190:193], v[50:53]
	v_mfma_i32_16x16x64_i8 v[46:49], v[136:139], v[198:201], v[46:49]
	v_mfma_i32_16x16x64_i8 v[42:45], v[158:161], v[198:201], v[42:45]
	v_mfma_i32_16x16x64_i8 v[38:41], v[136:139], v[206:209], v[38:41]
	v_mfma_i32_16x16x64_i8 v[34:37], v[158:161], v[206:209], v[34:37]
	v_mfma_i32_16x16x64_i8 v[62:65], v[140:143], v[186:189], v[62:65]
	v_mfma_i32_16x16x64_i8 v[58:61], v[162:165], v[186:189], v[58:61]
	v_mfma_i32_16x16x64_i8 v[54:57], v[140:143], v[194:197], v[54:57]
	v_mfma_i32_16x16x64_i8 v[50:53], v[162:165], v[194:197], v[50:53]
	v_mfma_i32_16x16x64_i8 v[46:49], v[140:143], v[202:205], v[46:49]
	v_mfma_i32_16x16x64_i8 v[42:45], v[162:165], v[202:205], v[42:45]
	v_mfma_i32_16x16x64_i8 v[38:41], v[140:143], v[210:213], v[38:41]
	v_mfma_i32_16x16x64_i8 v[34:37], v[162:165], v[210:213], v[34:37]
	v_mfma_i32_16x16x64_i8 v[30:33], v[166:169], v[182:185], v[30:33]
	v_mfma_i32_16x16x64_i8 v[26:29], v[174:177], v[182:185], v[26:29]
	v_mfma_i32_16x16x64_i8 v[22:25], v[166:169], v[190:193], v[22:25]
	v_mfma_i32_16x16x64_i8 v[18:21], v[174:177], v[190:193], v[18:21]
	v_mfma_i32_16x16x64_i8 v[14:17], v[166:169], v[198:201], v[14:17]
	v_mfma_i32_16x16x64_i8 v[10:13], v[174:177], v[198:201], v[10:13]
	v_mfma_i32_16x16x64_i8 v[6:9], v[166:169], v[206:209], v[6:9]
	v_mfma_i32_16x16x64_i8 v[2:5], v[174:177], v[206:209], v[2:5]
	v_mfma_i32_16x16x64_i8 v[30:33], v[170:173], v[186:189], v[30:33]
	v_mfma_i32_16x16x64_i8 v[26:29], v[178:181], v[186:189], v[26:29]
	v_mfma_i32_16x16x64_i8 v[22:25], v[170:173], v[194:197], v[22:25]
	v_mfma_i32_16x16x64_i8 v[18:21], v[178:181], v[194:197], v[18:21]
	v_mfma_i32_16x16x64_i8 v[14:17], v[170:173], v[202:205], v[14:17]
	v_mfma_i32_16x16x64_i8 v[10:13], v[178:181], v[202:205], v[10:13]
	v_mfma_i32_16x16x64_i8 v[6:9], v[170:173], v[210:213], v[6:9]
	v_mfma_i32_16x16x64_i8 v[2:5], v[178:181], v[210:213], v[2:5]
	s_setprio 0
	s_barrier
	s_add_i32 s59, s59, 2
	s_addk_i32 s55, 0x100
	s_addk_i32 s58, 0x100
	s_cmp_gt_u32 s59, 5
	s_cbranch_scc0 .LBB0_1072
	s_and_b64 vcc, exec, s[20:21]
	s_cbranch_vccz .LBB0_1075
	s_barrier

.LBB0_1135:
	v_add_u32_e32 v150, 0x10000, v136
	v_add_u32_e32 v166, 0x14000, v136
	ds_read_b128 v[138:141], v150
	ds_read_b128 v[142:145], v150 offset:1024
	ds_read_b128 v[146:149], v150 offset:2048
	ds_read_b128 v[150:153], v150 offset:3072
	ds_read_b128 v[154:157], v166
	ds_read_b128 v[158:161], v166 offset:1024
	ds_read_b128 v[162:165], v166 offset:2048
	ds_read_b128 v[166:169], v166 offset:3072
	s_add_i32 s57, s36, s3
	s_add_i32 s56, s30, s3
	s_add_i32 s55, s57, 0x1600
	s_addk_i32 s56, 0x1600
	s_cmp_eq_u32 s3, 0
	s_cselect_b32 s58, s53, s55
	s_cselect_b32 s56, s54, s56
	s_add_i32 s55, s58, 0x80
	s_add_i32 s57, s57, 0xb1580
	s_mov_b32 m0, s46
	s_nop 0
	buffer_load_dwordx4 v134, s[16:19], s57 offen lds
	s_nop 0
	s_mov_b32 m0, s47
	s_nop 0
	buffer_load_dwordx4 v135, s[16:19], s57 offen lds
	ds_read_b128 v[170:173], v137
	ds_read_b128 v[174:177], v137 offset:1024
	ds_read_b128 v[178:181], v137 offset:2048
	ds_read_b128 v[182:185], v137 offset:3072
	ds_read_b128 v[186:189], v137 offset:4096
	ds_read_b128 v[190:193], v137 offset:5120
	ds_read_b128 v[194:197], v137 offset:6144
	ds_read_b128 v[198:201], v137 offset:7168
	s_waitcnt vmcnt(8)
	s_waitcnt lgkmcnt(0)
	s_barrier
	s_setprio 1
	s_waitcnt lgkmcnt(7)
	v_mfma_f32_16x16x32_bf16 v[126:129], v[138:141], v[170:173], v[126:129]
	v_mfma_f32_16x16x32_bf16 v[122:125], v[146:149], v[170:173], v[122:125]
	s_waitcnt lgkmcnt(5)
	v_mfma_f32_16x16x32_bf16 v[118:121], v[138:141], v[178:181], v[118:121]
	v_mfma_f32_16x16x32_bf16 v[106:109], v[146:149], v[178:181], v[106:109]
	s_waitcnt lgkmcnt(3)
	v_mfma_f32_16x16x32_bf16 v[102:105], v[138:141], v[186:189], v[102:105]
	v_mfma_f32_16x16x32_bf16 v[90:93], v[146:149], v[186:189], v[90:93]
	s_waitcnt lgkmcnt(1)
	v_mfma_f32_16x16x32_bf16 v[86:89], v[138:141], v[194:197], v[86:89]
	v_mfma_f32_16x16x32_bf16 v[74:77], v[146:149], v[194:197], v[74:77]
	v_mfma_f32_16x16x32_bf16 v[126:129], v[142:145], v[174:177], v[126:129]
	v_mfma_f32_16x16x32_bf16 v[122:125], v[150:153], v[174:177], v[122:125]
	v_mfma_f32_16x16x32_bf16 v[118:121], v[142:145], v[182:185], v[118:121]
	v_mfma_f32_16x16x32_bf16 v[106:109], v[150:153], v[182:185], v[106:109]
	v_mfma_f32_16x16x32_bf16 v[102:105], v[142:145], v[190:193], v[102:105]
	v_mfma_f32_16x16x32_bf16 v[90:93], v[150:153], v[190:193], v[90:93]
	s_waitcnt lgkmcnt(0)
	v_mfma_f32_16x16x32_bf16 v[86:89], v[142:145], v[198:201], v[86:89]
	v_mfma_f32_16x16x32_bf16 v[74:77], v[150:153], v[198:201], v[74:77]
	v_mfma_f32_16x16x32_bf16 v[114:117], v[154:157], v[170:173], v[114:117]
	v_mfma_f32_16x16x32_bf16 v[110:113], v[162:165], v[170:173], v[110:113]
	v_mfma_f32_16x16x32_bf16 v[98:101], v[154:157], v[178:181], v[98:101]
	v_mfma_f32_16x16x32_bf16 v[94:97], v[162:165], v[178:181], v[94:97]
	v_mfma_f32_16x16x32_bf16 v[82:85], v[154:157], v[186:189], v[82:85]
	v_mfma_f32_16x16x32_bf16 v[78:81], v[162:165], v[186:189], v[78:81]
	v_mfma_f32_16x16x32_bf16 v[70:73], v[154:157], v[194:197], v[70:73]
	v_mfma_f32_16x16x32_bf16 v[66:69], v[162:165], v[194:197], v[66:69]
	v_mfma_f32_16x16x32_bf16 v[114:117], v[158:161], v[174:177], v[114:117]
	v_mfma_f32_16x16x32_bf16 v[110:113], v[166:169], v[174:177], v[110:113]
	v_mfma_f32_16x16x32_bf16 v[98:101], v[158:161], v[182:185], v[98:101]
	v_mfma_f32_16x16x32_bf16 v[94:97], v[166:169], v[182:185], v[94:97]
	v_mfma_f32_16x16x32_bf16 v[82:85], v[158:161], v[190:193], v[82:85]
	v_mfma_f32_16x16x32_bf16 v[78:81], v[166:169], v[190:193], v[78:81]
	v_mfma_f32_16x16x32_bf16 v[70:73], v[158:161], v[198:201], v[70:73]
	v_mfma_f32_16x16x32_bf16 v[66:69], v[166:169], v[198:201], v[66:69]
	s_setprio 0
	s_barrier
	ds_read_b128 v[170:173], v137 offset:16384
	ds_read_b128 v[174:177], v137 offset:17408
	s_mov_b32 m0, s29
	s_nop 0
	buffer_load_dwordx4 v134, s[12:15], s56 offen lds
	ds_read_b128 v[178:181], v137 offset:18432
	ds_read_b128 v[182:185], v137 offset:19456
	s_add_i32 s57, s56, 0xb0000
	s_mov_b32 m0, s33
	s_nop 0
	buffer_load_dwordx4 v135, s[12:15], s56 offen lds
	ds_read_b128 v[186:189], v137 offset:20480
	ds_read_b128 v[190:193], v137 offset:21504
	s_nop 0
	s_mov_b32 m0, s34
	s_nop 0
	buffer_load_dwordx4 v134, s[12:15], s57 offen lds
	ds_read_b128 v[194:197], v137 offset:22528
	ds_read_b128 v[198:201], v137 offset:23552
	s_nop 0
	s_mov_b32 m0, s35
	s_nop 0
	buffer_load_dwordx4 v135, s[12:15], s57 offen lds
	s_nop 0
	s_mov_b32 m0, s28
	s_nop 0
	buffer_load_dwordx4 v134, s[16:19], s58 offen lds
	s_nop 0
	s_mov_b32 m0, s37
	s_nop 0
	buffer_load_dwordx4 v135, s[16:19], s58 offen lds
	s_waitcnt vmcnt(8)
	s_waitcnt lgkmcnt(0)
	s_barrier
	s_setprio 1
	s_waitcnt lgkmcnt(7)
	v_mfma_f32_16x16x32_bf16 v[62:65], v[138:141], v[170:173], v[62:65]
	v_mfma_f32_16x16x32_bf16 v[58:61], v[146:149], v[170:173], v[58:61]
	s_waitcnt lgkmcnt(5)
	v_mfma_f32_16x16x32_bf16 v[54:57], v[138:141], v[178:181], v[54:57]
	v_mfma_f32_16x16x32_bf16 v[42:45], v[146:149], v[178:181], v[42:45]
	s_waitcnt lgkmcnt(3)
	v_mfma_f32_16x16x32_bf16 v[38:41], v[138:141], v[186:189], v[38:41]
	v_mfma_f32_16x16x32_bf16 v[26:29], v[146:149], v[186:189], v[26:29]
	s_waitcnt lgkmcnt(1)
	v_mfma_f32_16x16x32_bf16 v[18:21], v[138:141], v[194:197], v[18:21]
	v_mfma_f32_16x16x32_bf16 v[10:13], v[146:149], v[194:197], v[10:13]
	v_mfma_f32_16x16x32_bf16 v[62:65], v[142:145], v[174:177], v[62:65]
	v_mfma_f32_16x16x32_bf16 v[58:61], v[150:153], v[174:177], v[58:61]
	v_mfma_f32_16x16x32_bf16 v[54:57], v[142:145], v[182:185], v[54:57]
	v_mfma_f32_16x16x32_bf16 v[42:45], v[150:153], v[182:185], v[42:45]
	v_mfma_f32_16x16x32_bf16 v[38:41], v[142:145], v[190:193], v[38:41]
	v_mfma_f32_16x16x32_bf16 v[26:29], v[150:153], v[190:193], v[26:29]
	s_waitcnt lgkmcnt(0)
	v_mfma_f32_16x16x32_bf16 v[18:21], v[142:145], v[198:201], v[18:21]
	v_mfma_f32_16x16x32_bf16 v[10:13], v[150:153], v[198:201], v[10:13]
	v_mfma_f32_16x16x32_bf16 v[50:53], v[154:157], v[170:173], v[50:53]
	v_mfma_f32_16x16x32_bf16 v[46:49], v[162:165], v[170:173], v[46:49]
	v_mfma_f32_16x16x32_bf16 v[34:37], v[154:157], v[178:181], v[34:37]
	v_mfma_f32_16x16x32_bf16 v[30:33], v[162:165], v[178:181], v[30:33]
	v_mfma_f32_16x16x32_bf16 v[22:25], v[154:157], v[186:189], v[22:25]
	v_mfma_f32_16x16x32_bf16 v[14:17], v[162:165], v[186:189], v[14:17]
	v_mfma_f32_16x16x32_bf16 v[6:9], v[154:157], v[194:197], v[6:9]
	v_mfma_f32_16x16x32_bf16 v[2:5], v[162:165], v[194:197], v[2:5]
	v_mfma_f32_16x16x32_bf16 v[50:53], v[158:161], v[174:177], v[50:53]
	v_mfma_f32_16x16x32_bf16 v[46:49], v[166:169], v[174:177], v[46:49]
	v_mfma_f32_16x16x32_bf16 v[34:37], v[158:161], v[182:185], v[34:37]
	v_mfma_f32_16x16x32_bf16 v[30:33], v[166:169], v[182:185], v[30:33]
	v_mfma_f32_16x16x32_bf16 v[22:25], v[158:161], v[190:193], v[22:25]
	v_mfma_f32_16x16x32_bf16 v[14:17], v[166:169], v[190:193], v[14:17]
	v_mfma_f32_16x16x32_bf16 v[6:9], v[158:161], v[198:201], v[6:9]
	v_mfma_f32_16x16x32_bf16 v[2:5], v[166:169], v[198:201], v[2:5]
	s_setprio 0
	s_barrier
	v_add_u32_e32 v150, 0x18000, v136
	v_add_u32_e32 v166, 0x1c000, v136
	ds_read_b128 v[138:141], v150
	ds_read_b128 v[142:145], v150 offset:1024
	ds_read_b128 v[146:149], v150 offset:2048
	ds_read_b128 v[150:153], v150 offset:3072
	ds_read_b128 v[154:157], v166
	ds_read_b128 v[158:161], v166 offset:1024
	ds_read_b128 v[162:165], v166 offset:2048
	ds_read_b128 v[166:169], v166 offset:3072
	s_add_i32 s57, s58, 0xb0000
	s_mov_b32 m0, s38
	s_nop 0
	buffer_load_dwordx4 v134, s[16:19], s57 offen lds
	s_nop 0
	s_mov_b32 m0, s39
	s_nop 0
	buffer_load_dwordx4 v135, s[16:19], s57 offen lds
	ds_read_b128 v[170:173], v137 offset:32768
	ds_read_b128 v[174:177], v137 offset:33792
	ds_read_b128 v[178:181], v137 offset:34816
	ds_read_b128 v[182:185], v137 offset:35840
	ds_read_b128 v[186:189], v137 offset:36864
	ds_read_b128 v[190:193], v137 offset:37888
	ds_read_b128 v[194:197], v137 offset:38912
	ds_read_b128 v[198:201], v137 offset:39936
	s_waitcnt vmcnt(8)
	s_waitcnt lgkmcnt(0)
	s_barrier
	s_setprio 1
	s_waitcnt lgkmcnt(7)
	v_mfma_f32_16x16x32_bf16 v[126:129], v[138:141], v[170:173], v[126:129]
	v_mfma_f32_16x16x32_bf16 v[122:125], v[146:149], v[170:173], v[122:125]
	s_waitcnt lgkmcnt(5)
	v_mfma_f32_16x16x32_bf16 v[118:121], v[138:141], v[178:181], v[118:121]
	v_mfma_f32_16x16x32_bf16 v[106:109], v[146:149], v[178:181], v[106:109]
	s_waitcnt lgkmcnt(3)
	v_mfma_f32_16x16x32_bf16 v[102:105], v[138:141], v[186:189], v[102:105]
	v_mfma_f32_16x16x32_bf16 v[90:93], v[146:149], v[186:189], v[90:93]
	s_waitcnt lgkmcnt(1)
	v_mfma_f32_16x16x32_bf16 v[86:89], v[138:141], v[194:197], v[86:89]
	v_mfma_f32_16x16x32_bf16 v[74:77], v[146:149], v[194:197], v[74:77]
	v_mfma_f32_16x16x32_bf16 v[126:129], v[142:145], v[174:177], v[126:129]
	v_mfma_f32_16x16x32_bf16 v[122:125], v[150:153], v[174:177], v[122:125]
	v_mfma_f32_16x16x32_bf16 v[118:121], v[142:145], v[182:185], v[118:121]
	v_mfma_f32_16x16x32_bf16 v[106:109], v[150:153], v[182:185], v[106:109]
	v_mfma_f32_16x16x32_bf16 v[102:105], v[142:145], v[190:193], v[102:105]
	v_mfma_f32_16x16x32_bf16 v[90:93], v[150:153], v[190:193], v[90:93]
	s_waitcnt lgkmcnt(0)
	v_mfma_f32_16x16x32_bf16 v[86:89], v[142:145], v[198:201], v[86:89]
	v_mfma_f32_16x16x32_bf16 v[74:77], v[150:153], v[198:201], v[74:77]
	v_mfma_f32_16x16x32_bf16 v[114:117], v[154:157], v[170:173], v[114:117]
	v_mfma_f32_16x16x32_bf16 v[110:113], v[162:165], v[170:173], v[110:113]
	v_mfma_f32_16x16x32_bf16 v[98:101], v[154:157], v[178:181], v[98:101]
	v_mfma_f32_16x16x32_bf16 v[94:97], v[162:165], v[178:181], v[94:97]
	v_mfma_f32_16x16x32_bf16 v[82:85], v[154:157], v[186:189], v[82:85]
	v_mfma_f32_16x16x32_bf16 v[78:81], v[162:165], v[186:189], v[78:81]
	v_mfma_f32_16x16x32_bf16 v[70:73], v[154:157], v[194:197], v[70:73]
	v_mfma_f32_16x16x32_bf16 v[66:69], v[162:165], v[194:197], v[66:69]
	v_mfma_f32_16x16x32_bf16 v[114:117], v[158:161], v[174:177], v[114:117]
	v_mfma_f32_16x16x32_bf16 v[110:113], v[166:169], v[174:177], v[110:113]
	v_mfma_f32_16x16x32_bf16 v[98:101], v[158:161], v[182:185], v[98:101]
	v_mfma_f32_16x16x32_bf16 v[94:97], v[166:169], v[182:185], v[94:97]
	v_mfma_f32_16x16x32_bf16 v[82:85], v[158:161], v[190:193], v[82:85]
	v_mfma_f32_16x16x32_bf16 v[78:81], v[166:169], v[190:193], v[78:81]
	v_mfma_f32_16x16x32_bf16 v[70:73], v[158:161], v[198:201], v[70:73]
	v_mfma_f32_16x16x32_bf16 v[66:69], v[166:169], v[198:201], v[66:69]
	s_setprio 0
	s_barrier
	ds_read_b128 v[170:173], v137 offset:49152
	ds_read_b128 v[174:177], v137 offset:50176
	s_add_i32 s57, s56, 0x80
	s_mov_b32 m0, s40
	s_nop 0
	buffer_load_dwordx4 v134, s[12:15], s57 offen lds
	ds_read_b128 v[178:181], v137 offset:51200
	ds_read_b128 v[182:185], v137 offset:52224
	s_add_i32 s56, s56, 0xb0080
	s_mov_b32 m0, s41
	s_nop 0
	buffer_load_dwordx4 v135, s[12:15], s57 offen lds
	ds_read_b128 v[186:189], v137 offset:53248
	ds_read_b128 v[190:193], v137 offset:54272
	s_nop 0
	s_mov_b32 m0, s44
	s_nop 0
	buffer_load_dwordx4 v134, s[12:15], s56 offen lds
	ds_read_b128 v[194:197], v137 offset:55296
	ds_read_b128 v[198:201], v137 offset:56320
	s_nop 0
	s_mov_b32 m0, s45
	s_nop 0
	buffer_load_dwordx4 v135, s[12:15], s56 offen lds
	s_nop 0
	s_mov_b32 m0, s42
	s_nop 0
	buffer_load_dwordx4 v134, s[16:19], s55 offen lds
	s_nop 0
	s_mov_b32 m0, s43
	s_nop 0
	buffer_load_dwordx4 v135, s[16:19], s55 offen lds
	s_waitcnt vmcnt(8)
	s_waitcnt lgkmcnt(0)
	s_barrier
	s_setprio 1
	s_waitcnt lgkmcnt(7)
	v_mfma_f32_16x16x32_bf16 v[62:65], v[138:141], v[170:173], v[62:65]
	v_mfma_f32_16x16x32_bf16 v[58:61], v[146:149], v[170:173], v[58:61]
	s_waitcnt lgkmcnt(5)
	v_mfma_f32_16x16x32_bf16 v[54:57], v[138:141], v[178:181], v[54:57]
	v_mfma_f32_16x16x32_bf16 v[42:45], v[146:149], v[178:181], v[42:45]
	s_waitcnt lgkmcnt(3)
	v_mfma_f32_16x16x32_bf16 v[38:41], v[138:141], v[186:189], v[38:41]
	v_mfma_f32_16x16x32_bf16 v[26:29], v[146:149], v[186:189], v[26:29]
	s_waitcnt lgkmcnt(1)
	v_mfma_f32_16x16x32_bf16 v[18:21], v[138:141], v[194:197], v[18:21]
	v_mfma_f32_16x16x32_bf16 v[10:13], v[146:149], v[194:197], v[10:13]
	v_mfma_f32_16x16x32_bf16 v[62:65], v[142:145], v[174:177], v[62:65]
	v_mfma_f32_16x16x32_bf16 v[58:61], v[150:153], v[174:177], v[58:61]
	v_mfma_f32_16x16x32_bf16 v[54:57], v[142:145], v[182:185], v[54:57]
	v_mfma_f32_16x16x32_bf16 v[42:45], v[150:153], v[182:185], v[42:45]
	v_mfma_f32_16x16x32_bf16 v[38:41], v[142:145], v[190:193], v[38:41]
	v_mfma_f32_16x16x32_bf16 v[26:29], v[150:153], v[190:193], v[26:29]
	s_waitcnt lgkmcnt(0)
	v_mfma_f32_16x16x32_bf16 v[18:21], v[142:145], v[198:201], v[18:21]
	v_mfma_f32_16x16x32_bf16 v[10:13], v[150:153], v[198:201], v[10:13]
	v_mfma_f32_16x16x32_bf16 v[50:53], v[154:157], v[170:173], v[50:53]
	v_mfma_f32_16x16x32_bf16 v[46:49], v[162:165], v[170:173], v[46:49]
	v_mfma_f32_16x16x32_bf16 v[34:37], v[154:157], v[178:181], v[34:37]
	v_mfma_f32_16x16x32_bf16 v[30:33], v[162:165], v[178:181], v[30:33]
	v_mfma_f32_16x16x32_bf16 v[22:25], v[154:157], v[186:189], v[22:25]
	v_mfma_f32_16x16x32_bf16 v[14:17], v[162:165], v[186:189], v[14:17]
	v_mfma_f32_16x16x32_bf16 v[6:9], v[154:157], v[194:197], v[6:9]
	v_mfma_f32_16x16x32_bf16 v[2:5], v[162:165], v[194:197], v[2:5]
	v_mfma_f32_16x16x32_bf16 v[50:53], v[158:161], v[174:177], v[50:53]
	v_mfma_f32_16x16x32_bf16 v[46:49], v[166:169], v[174:177], v[46:49]
	v_mfma_f32_16x16x32_bf16 v[34:37], v[158:161], v[182:185], v[34:37]
	v_mfma_f32_16x16x32_bf16 v[30:33], v[166:169], v[182:185], v[30:33]
	v_mfma_f32_16x16x32_bf16 v[22:25], v[158:161], v[190:193], v[22:25]
	v_mfma_f32_16x16x32_bf16 v[14:17], v[166:169], v[190:193], v[14:17]
	v_mfma_f32_16x16x32_bf16 v[6:9], v[158:161], v[198:201], v[6:9]
	v_mfma_f32_16x16x32_bf16 v[2:5], v[166:169], v[198:201], v[2:5]
	s_setprio 0
	s_barrier
	s_add_i32 s2, s2, 2
	s_addk_i32 s3, 0x100
	s_cmp_gt_u32 s2, 41
	s_cbranch_scc0 .LBB0_1135
	s_andn2_b64 vcc, exec, s[4:5]
	s_cbranch_vccnz .LBB0_1123
	v_mov_b32_e32 v2, 0
	s_mov_b32 s20, s50
	s_mov_b32 s25, s51
	s_mov_b32 s30, s54
	s_mov_b32 s36, s53
	s_mov_b32 s49, s52
	v_mov_b32_e32 v3, v2
	v_mov_b32_e32 v4, v2
	v_mov_b32_e32 v5, v2
	v_mov_b32_e32 v6, v2
	v_mov_b32_e32 v7, v2
	v_mov_b32_e32 v8, v2
	v_mov_b32_e32 v9, v2
	v_mov_b32_e32 v14, v2
	v_mov_b32_e32 v15, v2
	v_mov_b32_e32 v16, v2
	v_mov_b32_e32 v17, v2
	v_mov_b32_e32 v22, v2
	v_mov_b32_e32 v23, v2
	v_mov_b32_e32 v24, v2
	v_mov_b32_e32 v25, v2
	v_mov_b32_e32 v30, v2
	v_mov_b32_e32 v31, v2
	v_mov_b32_e32 v32, v2
	v_mov_b32_e32 v33, v2
	v_mov_b32_e32 v34, v2
	v_mov_b32_e32 v35, v2
	v_mov_b32_e32 v36, v2
	v_mov_b32_e32 v37, v2
	v_mov_b32_e32 v46, v2
	v_mov_b32_e32 v47, v2
	v_mov_b32_e32 v48, v2
	v_mov_b32_e32 v49, v2
	v_mov_b32_e32 v50, v2
	v_mov_b32_e32 v51, v2
	v_mov_b32_e32 v52, v2
	v_mov_b32_e32 v53, v2
	v_mov_b32_e32 v10, v2
	v_mov_b32_e32 v11, v2
	v_mov_b32_e32 v12, v2
	v_mov_b32_e32 v13, v2
	v_mov_b32_e32 v18, v2
	v_mov_b32_e32 v19, v2
	v_mov_b32_e32 v20, v2
	v_mov_b32_e32 v21, v2
	v_mov_b32_e32 v26, v2
	v_mov_b32_e32 v27, v2
	v_mov_b32_e32 v28, v2
	v_mov_b32_e32 v29, v2
	v_mov_b32_e32 v38, v2
	v_mov_b32_e32 v39, v2
	v_mov_b32_e32 v40, v2
	v_mov_b32_e32 v41, v2
	v_mov_b32_e32 v42, v2
	v_mov_b32_e32 v43, v2
	v_mov_b32_e32 v44, v2
	v_mov_b32_e32 v45, v2
	v_mov_b32_e32 v54, v2
	v_mov_b32_e32 v55, v2
	v_mov_b32_e32 v56, v2
	v_mov_b32_e32 v57, v2
	v_mov_b32_e32 v58, v2
	v_mov_b32_e32 v59, v2
	v_mov_b32_e32 v60, v2
	v_mov_b32_e32 v61, v2
	v_mov_b32_e32 v62, v2
	v_mov_b32_e32 v63, v2
	v_mov_b32_e32 v64, v2
	v_mov_b32_e32 v65, v2
	v_mov_b32_e32 v66, v2
	v_mov_b32_e32 v67, v2
	v_mov_b32_e32 v68, v2
	v_mov_b32_e32 v69, v2
	v_mov_b32_e32 v70, v2
	v_mov_b32_e32 v71, v2
	v_mov_b32_e32 v72, v2
	v_mov_b32_e32 v73, v2
	v_mov_b32_e32 v78, v2
	v_mov_b32_e32 v79, v2
	v_mov_b32_e32 v80, v2
	v_mov_b32_e32 v81, v2
	v_mov_b32_e32 v82, v2
	v_mov_b32_e32 v83, v2
	v_mov_b32_e32 v84, v2
	v_mov_b32_e32 v85, v2
	v_mov_b32_e32 v94, v2
	v_mov_b32_e32 v95, v2
	v_mov_b32_e32 v96, v2
	v_mov_b32_e32 v97, v2
	v_mov_b32_e32 v98, v2
	v_mov_b32_e32 v99, v2
	v_mov_b32_e32 v100, v2
	v_mov_b32_e32 v101, v2
	v_mov_b32_e32 v110, v2
	v_mov_b32_e32 v111, v2
	v_mov_b32_e32 v112, v2
	v_mov_b32_e32 v113, v2
	v_mov_b32_e32 v114, v2
	v_mov_b32_e32 v115, v2
	v_mov_b32_e32 v116, v2
	v_mov_b32_e32 v117, v2
	v_mov_b32_e32 v74, v2
	v_mov_b32_e32 v75, v2
	v_mov_b32_e32 v76, v2
	v_mov_b32_e32 v77, v2
	v_mov_b32_e32 v86, v2
	v_mov_b32_e32 v87, v2
	v_mov_b32_e32 v88, v2
	v_mov_b32_e32 v89, v2
	v_mov_b32_e32 v90, v2
	v_mov_b32_e32 v91, v2
	v_mov_b32_e32 v92, v2
	v_mov_b32_e32 v93, v2
	v_mov_b32_e32 v102, v2
	v_mov_b32_e32 v103, v2
	v_mov_b32_e32 v104, v2
	v_mov_b32_e32 v105, v2
	v_mov_b32_e32 v106, v2
	v_mov_b32_e32 v107, v2
	v_mov_b32_e32 v108, v2
	v_mov_b32_e32 v109, v2
	v_mov_b32_e32 v118, v2
	v_mov_b32_e32 v119, v2
	v_mov_b32_e32 v120, v2
	v_mov_b32_e32 v121, v2
	v_mov_b32_e32 v122, v2
	v_mov_b32_e32 v123, v2
	v_mov_b32_e32 v124, v2
	v_mov_b32_e32 v125, v2
	v_mov_b32_e32 v126, v2
	v_mov_b32_e32 v127, v2
	v_mov_b32_e32 v128, v2
	v_mov_b32_e32 v129, v2
	s_branch .LBB0_1123
